# scan consumer: operand loads for two steps issued together, one lgkmcnt wait per two steps
# baseline (speedup 1.0000x reference)
.Lscan_cons_chunk:
	v_cndmask_b32_e64 v2, v4, v5, s[42:43]
	v_add_lshl_u32 v2, v2, s80, 10
	v_mov_b32_e32 v3, v180
	s_add_i32 s28, s28, 0x10000
	v_lshl_add_u64 v[2:3], v[0:1], 0, v[2:3]
	v_add_u32_e32 v5, 64, v5
	v_subrev_u32_e32 v4, 64, v4
	s_waitcnt lgkmcnt(0)
	v_fma_mix_f32 v12, v6, v20, v180 op_sel_hi:[0,1,0]
	v_fma_mix_f32 v12, v7, v20, v12 op_sel:[0,1,0] op_sel_hi:[0,1,0]
	v_fma_mix_f32 v12, v8, v21, v12 op_sel_hi:[0,1,0]
	v_fma_mix_f32 v12, v9, v21, v12 op_sel:[0,1,0] op_sel_hi:[0,1,0]
	v_pk_mul_f32 v[48:49], v[6:7], v[16:17]
	v_pk_mul_f32 v[50:51], v[8:9], v[18:19]
	v_add_f32_dpp v12, v12, v12 row_ror:1 row_mask:0xf bank_mask:0xf bound_ctrl:1
	s_nop 1
	v_add_f32_dpp v12, v12, v12 row_ror:2 row_mask:0xf bank_mask:0xf bound_ctrl:1
	v_pk_fma_f32 v[48:49], v[28:29], v[66:67], v[48:49] op_sel_hi:[1,0,1]
	v_pk_fma_f32 v[50:51], v[30:31], v[66:67], v[50:51] op_sel_hi:[1,0,1]
	v_add_f32_dpp v12, v12, v12 row_ror:4 row_mask:0xf bank_mask:0xf bound_ctrl:1
	s_nop 1
	v_add_f32_dpp v12, v12, v12 row_ror:8 row_mask:0xf bank_mask:0xf bound_ctrl:1
	v_pk_fma_f32 v[6:7], v[24:25], v[12:13], v[48:49] op_sel_hi:[1,0,1] neg_lo:[1,0,0] neg_hi:[1,0,0]
	v_pk_fma_f32 v[8:9], v[26:27], v[12:13], v[50:51] op_sel_hi:[1,0,1] neg_lo:[1,0,0] neg_hi:[1,0,0]
	ds_read_b128 v[88:91], v10 offset:2304
	ds_read_b128 v[84:87], v10 offset:2048
	ds_read_b128 v[96:99], v10 offset:2816
	ds_read_b128 v[92:95], v10 offset:2560
	ds_read_b128 v[110:113], v10 offset:3328
	ds_read_b128 v[106:109], v10 offset:3072
	ds_read_b128 v[118:121], v10 offset:3840
	ds_read_b128 v[114:117], v10 offset:3584
	ds_read_b128 v[70:73], v11 offset:256
	v_fma_mix_f32 v12, v6, v36, v180 op_sel_hi:[0,1,0]
	v_fma_mix_f32 v12, v7, v36, v12 op_sel:[0,1,0] op_sel_hi:[0,1,0]
	v_fma_mix_f32 v12, v8, v37, v12 op_sel_hi:[0,1,0]
	v_fma_mix_f32 v12, v9, v37, v12 op_sel:[0,1,0] op_sel_hi:[0,1,0]
	v_pk_mul_f32 v[48:49], v[6:7], v[32:33]
	v_pk_mul_f32 v[50:51], v[8:9], v[34:35]
	v_add_f32_dpp v12, v12, v12 row_ror:1 row_mask:0xf bank_mask:0xf bound_ctrl:1
	v_fma_mix_f32 v52, v6, v22, v180 op_sel_hi:[0,1,0]
	v_fma_mix_f32 v52, v7, v22, v52 op_sel:[0,1,0] op_sel_hi:[0,1,0]
	v_add_f32_dpp v12, v12, v12 row_ror:2 row_mask:0xf bank_mask:0xf bound_ctrl:1
	v_pk_fma_f32 v[48:49], v[44:45], v[66:67], v[48:49] op_sel:[0,1,0]
	v_pk_fma_f32 v[50:51], v[46:47], v[66:67], v[50:51] op_sel:[0,1,0]
	v_add_f32_dpp v12, v12, v12 row_ror:4 row_mask:0xf bank_mask:0xf bound_ctrl:1
	v_fma_mix_f32 v52, v8, v23, v52 op_sel_hi:[0,1,0]
	v_fma_mix_f32 v52, v9, v23, v52 op_sel:[0,1,0] op_sel_hi:[0,1,0]
	v_add_f32_dpp v12, v12, v12 row_ror:8 row_mask:0xf bank_mask:0xf bound_ctrl:1
	v_pk_fma_f32 v[6:7], v[40:41], v[12:13], v[48:49] op_sel_hi:[1,0,1] neg_lo:[1,0,0] neg_hi:[1,0,0]
	v_pk_fma_f32 v[8:9], v[42:43], v[12:13], v[50:51] op_sel_hi:[1,0,1] neg_lo:[1,0,0] neg_hi:[1,0,0]
	s_waitcnt lgkmcnt(1)
	v_fma_mix_f32 v12, v6, v88, v180 op_sel_hi:[0,1,0]
	v_fma_mix_f32 v12, v7, v88, v12 op_sel:[0,1,0] op_sel_hi:[0,1,0]
	v_fma_mix_f32 v12, v8, v89, v12 op_sel_hi:[0,1,0]
	v_fma_mix_f32 v12, v9, v89, v12 op_sel:[0,1,0] op_sel_hi:[0,1,0]
	v_pk_mul_f32 v[48:49], v[6:7], v[84:85]
	v_pk_mul_f32 v[50:51], v[8:9], v[86:87]
	v_add_f32_dpp v12, v12, v12 row_ror:1 row_mask:0xf bank_mask:0xf bound_ctrl:1
	v_fma_mix_f32 v53, v6, v38, v180 op_sel_hi:[0,1,0]
	v_fma_mix_f32 v53, v7, v38, v53 op_sel:[0,1,0] op_sel_hi:[0,1,0]
	v_add_f32_dpp v12, v12, v12 row_ror:2 row_mask:0xf bank_mask:0xf bound_ctrl:1
	v_pk_fma_f32 v[48:49], v[96:97], v[68:69], v[48:49] op_sel_hi:[1,0,1]
	v_pk_fma_f32 v[50:51], v[98:99], v[68:69], v[50:51] op_sel_hi:[1,0,1]
	v_add_f32_dpp v12, v12, v12 row_ror:4 row_mask:0xf bank_mask:0xf bound_ctrl:1
	v_fma_mix_f32 v53, v8, v39, v53 op_sel_hi:[0,1,0]
	v_fma_mix_f32 v53, v9, v39, v53 op_sel:[0,1,0] op_sel_hi:[0,1,0]
	v_add_f32_dpp v12, v12, v12 row_ror:8 row_mask:0xf bank_mask:0xf bound_ctrl:1
	v_pk_fma_f32 v[6:7], v[92:93], v[12:13], v[48:49] op_sel_hi:[1,0,1] neg_lo:[1,0,0] neg_hi:[1,0,0]
	v_pk_fma_f32 v[8:9], v[94:95], v[12:13], v[50:51] op_sel_hi:[1,0,1] neg_lo:[1,0,0] neg_hi:[1,0,0]
	ds_read_b128 v[20:23], v10 offset:4352
	ds_read_b128 v[16:19], v10 offset:4096
	ds_read_b128 v[28:31], v10 offset:4864
	ds_read_b128 v[24:27], v10 offset:4608
	ds_read_b128 v[36:39], v10 offset:5376
	ds_read_b128 v[32:35], v10 offset:5120
	ds_read_b128 v[44:47], v10 offset:5888
	ds_read_b128 v[40:43], v10 offset:5632
	v_fma_mix_f32 v12, v6, v110, v180 op_sel_hi:[0,1,0]
	v_fma_mix_f32 v12, v7, v110, v12 op_sel:[0,1,0] op_sel_hi:[0,1,0]
	v_fma_mix_f32 v12, v8, v111, v12 op_sel_hi:[0,1,0]
	v_fma_mix_f32 v12, v9, v111, v12 op_sel:[0,1,0] op_sel_hi:[0,1,0]
	v_pk_mul_f32 v[48:49], v[6:7], v[106:107]
	v_pk_mul_f32 v[50:51], v[8:9], v[108:109]
	v_add_f32_dpp v12, v12, v12 row_ror:1 row_mask:0xf bank_mask:0xf bound_ctrl:1
	v_fma_mix_f32 v54, v6, v90, v180 op_sel_hi:[0,1,0]
	v_fma_mix_f32 v54, v7, v90, v54 op_sel:[0,1,0] op_sel_hi:[0,1,0]
	v_add_f32_dpp v12, v12, v12 row_ror:2 row_mask:0xf bank_mask:0xf bound_ctrl:1
	v_pk_fma_f32 v[48:49], v[118:119], v[68:69], v[48:49] op_sel:[0,1,0]
	v_pk_fma_f32 v[50:51], v[120:121], v[68:69], v[50:51] op_sel:[0,1,0]
	v_add_f32_dpp v12, v12, v12 row_ror:4 row_mask:0xf bank_mask:0xf bound_ctrl:1
	v_fma_mix_f32 v54, v8, v91, v54 op_sel_hi:[0,1,0]
	v_fma_mix_f32 v54, v9, v91, v54 op_sel:[0,1,0] op_sel_hi:[0,1,0]
	v_add_f32_dpp v12, v12, v12 row_ror:8 row_mask:0xf bank_mask:0xf bound_ctrl:1
	v_pk_fma_f32 v[6:7], v[114:115], v[12:13], v[48:49] op_sel_hi:[1,0,1] neg_lo:[1,0,0] neg_hi:[1,0,0]
	v_pk_fma_f32 v[8:9], v[116:117], v[12:13], v[50:51] op_sel_hi:[1,0,1] neg_lo:[1,0,0] neg_hi:[1,0,0]
	s_waitcnt lgkmcnt(0)
	v_fma_mix_f32 v12, v6, v20, v180 op_sel_hi:[0,1,0]
	v_fma_mix_f32 v12, v7, v20, v12 op_sel:[0,1,0] op_sel_hi:[0,1,0]
	v_fma_mix_f32 v12, v8, v21, v12 op_sel_hi:[0,1,0]
	v_fma_mix_f32 v12, v9, v21, v12 op_sel:[0,1,0] op_sel_hi:[0,1,0]
	v_pk_mul_f32 v[48:49], v[6:7], v[16:17]
	v_pk_mul_f32 v[50:51], v[8:9], v[18:19]
	v_add_f32_dpp v12, v12, v12 row_ror:1 row_mask:0xf bank_mask:0xf bound_ctrl:1
	v_fma_mix_f32 v55, v6, v112, v180 op_sel_hi:[0,1,0]
	v_fma_mix_f32 v55, v7, v112, v55 op_sel:[0,1,0] op_sel_hi:[0,1,0]
	v_add_f32_dpp v12, v12, v12 row_ror:2 row_mask:0xf bank_mask:0xf bound_ctrl:1
	v_pk_fma_f32 v[48:49], v[28:29], v[70:71], v[48:49] op_sel_hi:[1,0,1]
	v_pk_fma_f32 v[50:51], v[30:31], v[70:71], v[50:51] op_sel_hi:[1,0,1]
	v_add_f32_dpp v12, v12, v12 row_ror:4 row_mask:0xf bank_mask:0xf bound_ctrl:1
	v_fma_mix_f32 v55, v8, v113, v55 op_sel_hi:[0,1,0]
	v_fma_mix_f32 v55, v9, v113, v55 op_sel:[0,1,0] op_sel_hi:[0,1,0]
	v_add_f32_dpp v12, v12, v12 row_ror:8 row_mask:0xf bank_mask:0xf bound_ctrl:1
	v_pk_fma_f32 v[6:7], v[24:25], v[12:13], v[48:49] op_sel_hi:[1,0,1] neg_lo:[1,0,0] neg_hi:[1,0,0]
	v_pk_fma_f32 v[8:9], v[26:27], v[12:13], v[50:51] op_sel_hi:[1,0,1] neg_lo:[1,0,0] neg_hi:[1,0,0]
	ds_read_b128 v[88:91], v10 offset:6400
	ds_read_b128 v[84:87], v10 offset:6144
	ds_read_b128 v[96:99], v10 offset:6912
	ds_read_b128 v[92:95], v10 offset:6656
	ds_read_b128 v[110:113], v10 offset:7424
	ds_read_b128 v[106:109], v10 offset:7168
	ds_read_b128 v[118:121], v10 offset:7936
	ds_read_b128 v[114:117], v10 offset:7680
	ds_read_b128 v[66:69], v11 offset:512
	v_fma_mix_f32 v12, v6, v36, v180 op_sel_hi:[0,1,0]
	v_fma_mix_f32 v12, v7, v36, v12 op_sel:[0,1,0] op_sel_hi:[0,1,0]
	v_fma_mix_f32 v12, v8, v37, v12 op_sel_hi:[0,1,0]
	v_fma_mix_f32 v12, v9, v37, v12 op_sel:[0,1,0] op_sel_hi:[0,1,0]
	v_pk_mul_f32 v[48:49], v[6:7], v[32:33]
	v_pk_mul_f32 v[50:51], v[8:9], v[34:35]
	v_add_f32_dpp v12, v12, v12 row_ror:1 row_mask:0xf bank_mask:0xf bound_ctrl:1
	v_fma_mix_f32 v56, v6, v22, v180 op_sel_hi:[0,1,0]
	v_fma_mix_f32 v56, v7, v22, v56 op_sel:[0,1,0] op_sel_hi:[0,1,0]
	v_add_f32_dpp v12, v12, v12 row_ror:2 row_mask:0xf bank_mask:0xf bound_ctrl:1
	v_pk_fma_f32 v[48:49], v[44:45], v[70:71], v[48:49] op_sel:[0,1,0]
	v_pk_fma_f32 v[50:51], v[46:47], v[70:71], v[50:51] op_sel:[0,1,0]
	v_add_f32_dpp v12, v12, v12 row_ror:4 row_mask:0xf bank_mask:0xf bound_ctrl:1
	v_fma_mix_f32 v56, v8, v23, v56 op_sel_hi:[0,1,0]
	v_fma_mix_f32 v56, v9, v23, v56 op_sel:[0,1,0] op_sel_hi:[0,1,0]
	v_add_f32_dpp v12, v12, v12 row_ror:8 row_mask:0xf bank_mask:0xf bound_ctrl:1
	v_pk_fma_f32 v[6:7], v[40:41], v[12:13], v[48:49] op_sel_hi:[1,0,1] neg_lo:[1,0,0] neg_hi:[1,0,0]
	v_pk_fma_f32 v[8:9], v[42:43], v[12:13], v[50:51] op_sel_hi:[1,0,1] neg_lo:[1,0,0] neg_hi:[1,0,0]
	s_waitcnt lgkmcnt(1)
	v_fma_mix_f32 v12, v6, v88, v180 op_sel_hi:[0,1,0]
	v_fma_mix_f32 v12, v7, v88, v12 op_sel:[0,1,0] op_sel_hi:[0,1,0]
	v_fma_mix_f32 v12, v8, v89, v12 op_sel_hi:[0,1,0]
	v_fma_mix_f32 v12, v9, v89, v12 op_sel:[0,1,0] op_sel_hi:[0,1,0]
	v_pk_mul_f32 v[48:49], v[6:7], v[84:85]
	v_pk_mul_f32 v[50:51], v[8:9], v[86:87]
	v_add_f32_dpp v12, v12, v12 row_ror:1 row_mask:0xf bank_mask:0xf bound_ctrl:1
	v_fma_mix_f32 v57, v6, v38, v180 op_sel_hi:[0,1,0]
	v_fma_mix_f32 v57, v7, v38, v57 op_sel:[0,1,0] op_sel_hi:[0,1,0]
	v_add_f32_dpp v12, v12, v12 row_ror:2 row_mask:0xf bank_mask:0xf bound_ctrl:1
	v_pk_fma_f32 v[48:49], v[96:97], v[72:73], v[48:49] op_sel_hi:[1,0,1]
	v_pk_fma_f32 v[50:51], v[98:99], v[72:73], v[50:51] op_sel_hi:[1,0,1]
	v_add_f32_dpp v12, v12, v12 row_ror:4 row_mask:0xf bank_mask:0xf bound_ctrl:1
	v_fma_mix_f32 v57, v8, v39, v57 op_sel_hi:[0,1,0]
	v_fma_mix_f32 v57, v9, v39, v57 op_sel:[0,1,0] op_sel_hi:[0,1,0]
	v_add_f32_dpp v12, v12, v12 row_ror:8 row_mask:0xf bank_mask:0xf bound_ctrl:1
	v_pk_fma_f32 v[6:7], v[92:93], v[12:13], v[48:49] op_sel_hi:[1,0,1] neg_lo:[1,0,0] neg_hi:[1,0,0]
	v_pk_fma_f32 v[8:9], v[94:95], v[12:13], v[50:51] op_sel_hi:[1,0,1] neg_lo:[1,0,0] neg_hi:[1,0,0]
	ds_read_b128 v[20:23], v10 offset:8448
	ds_read_b128 v[16:19], v10 offset:8192
	ds_read_b128 v[28:31], v10 offset:8960
	ds_read_b128 v[24:27], v10 offset:8704
	ds_read_b128 v[36:39], v10 offset:9472
	ds_read_b128 v[32:35], v10 offset:9216
	ds_read_b128 v[44:47], v10 offset:9984
	ds_read_b128 v[40:43], v10 offset:9728
	v_fma_mix_f32 v12, v6, v110, v180 op_sel_hi:[0,1,0]
	v_fma_mix_f32 v12, v7, v110, v12 op_sel:[0,1,0] op_sel_hi:[0,1,0]
	v_fma_mix_f32 v12, v8, v111, v12 op_sel_hi:[0,1,0]
	v_fma_mix_f32 v12, v9, v111, v12 op_sel:[0,1,0] op_sel_hi:[0,1,0]
	v_pk_mul_f32 v[48:49], v[6:7], v[106:107]
	v_pk_mul_f32 v[50:51], v[8:9], v[108:109]
	v_add_f32_dpp v12, v12, v12 row_ror:1 row_mask:0xf bank_mask:0xf bound_ctrl:1
	v_fma_mix_f32 v81, v6, v90, v180 op_sel_hi:[0,1,0]
	v_fma_mix_f32 v81, v7, v90, v81 op_sel:[0,1,0] op_sel_hi:[0,1,0]
	v_add_f32_dpp v12, v12, v12 row_ror:2 row_mask:0xf bank_mask:0xf bound_ctrl:1
	v_pk_fma_f32 v[48:49], v[118:119], v[72:73], v[48:49] op_sel:[0,1,0]
	v_pk_fma_f32 v[50:51], v[120:121], v[72:73], v[50:51] op_sel:[0,1,0]
	v_add_f32_dpp v12, v12, v12 row_ror:4 row_mask:0xf bank_mask:0xf bound_ctrl:1
	v_fma_mix_f32 v81, v8, v91, v81 op_sel_hi:[0,1,0]
	v_fma_mix_f32 v81, v9, v91, v81 op_sel:[0,1,0] op_sel_hi:[0,1,0]
	v_add_f32_dpp v12, v12, v12 row_ror:8 row_mask:0xf bank_mask:0xf bound_ctrl:1
	v_pk_fma_f32 v[6:7], v[114:115], v[12:13], v[48:49] op_sel_hi:[1,0,1] neg_lo:[1,0,0] neg_hi:[1,0,0]
	v_pk_fma_f32 v[8:9], v[116:117], v[12:13], v[50:51] op_sel_hi:[1,0,1] neg_lo:[1,0,0] neg_hi:[1,0,0]
	s_waitcnt lgkmcnt(0)
	v_fma_mix_f32 v12, v6, v20, v180 op_sel_hi:[0,1,0]
	v_fma_mix_f32 v12, v7, v20, v12 op_sel:[0,1,0] op_sel_hi:[0,1,0]
	v_fma_mix_f32 v12, v8, v21, v12 op_sel_hi:[0,1,0]
	v_fma_mix_f32 v12, v9, v21, v12 op_sel:[0,1,0] op_sel_hi:[0,1,0]
	v_pk_mul_f32 v[48:49], v[6:7], v[16:17]
	v_pk_mul_f32 v[50:51], v[8:9], v[18:19]
	v_add_f32_dpp v12, v12, v12 row_ror:1 row_mask:0xf bank_mask:0xf bound_ctrl:1
	v_fma_mix_f32 v82, v6, v112, v180 op_sel_hi:[0,1,0]
	v_fma_mix_f32 v82, v7, v112, v82 op_sel:[0,1,0] op_sel_hi:[0,1,0]
	v_add_f32_dpp v12, v12, v12 row_ror:2 row_mask:0xf bank_mask:0xf bound_ctrl:1
	v_pk_fma_f32 v[48:49], v[28:29], v[66:67], v[48:49] op_sel_hi:[1,0,1]
	v_pk_fma_f32 v[50:51], v[30:31], v[66:67], v[50:51] op_sel_hi:[1,0,1]
	v_add_f32_dpp v12, v12, v12 row_ror:4 row_mask:0xf bank_mask:0xf bound_ctrl:1
	v_fma_mix_f32 v82, v8, v113, v82 op_sel_hi:[0,1,0]
	v_fma_mix_f32 v82, v9, v113, v82 op_sel:[0,1,0] op_sel_hi:[0,1,0]
	v_add_f32_dpp v12, v12, v12 row_ror:8 row_mask:0xf bank_mask:0xf bound_ctrl:1
	v_pk_fma_f32 v[6:7], v[24:25], v[12:13], v[48:49] op_sel_hi:[1,0,1] neg_lo:[1,0,0] neg_hi:[1,0,0]
	v_pk_fma_f32 v[8:9], v[26:27], v[12:13], v[50:51] op_sel_hi:[1,0,1] neg_lo:[1,0,0] neg_hi:[1,0,0]
	ds_read_b128 v[88:91], v10 offset:10496
	ds_read_b128 v[84:87], v10 offset:10240
	ds_read_b128 v[96:99], v10 offset:11008
	ds_read_b128 v[92:95], v10 offset:10752
	ds_read_b128 v[110:113], v10 offset:11520
	ds_read_b128 v[106:109], v10 offset:11264
	ds_read_b128 v[118:121], v10 offset:12032
	ds_read_b128 v[114:117], v10 offset:11776
	ds_read_b128 v[70:73], v11 offset:768
	v_fma_mix_f32 v12, v6, v36, v180 op_sel_hi:[0,1,0]
	v_fma_mix_f32 v12, v7, v36, v12 op_sel:[0,1,0] op_sel_hi:[0,1,0]
	v_fma_mix_f32 v12, v8, v37, v12 op_sel_hi:[0,1,0]
	v_fma_mix_f32 v12, v9, v37, v12 op_sel:[0,1,0] op_sel_hi:[0,1,0]
	v_pk_mul_f32 v[48:49], v[6:7], v[32:33]
	v_pk_mul_f32 v[50:51], v[8:9], v[34:35]
	v_add_f32_dpp v12, v12, v12 row_ror:1 row_mask:0xf bank_mask:0xf bound_ctrl:1
	v_fma_mix_f32 v83, v6, v22, v180 op_sel_hi:[0,1,0]
	v_fma_mix_f32 v83, v7, v22, v83 op_sel:[0,1,0] op_sel_hi:[0,1,0]
	v_add_f32_dpp v12, v12, v12 row_ror:2 row_mask:0xf bank_mask:0xf bound_ctrl:1
	v_pk_fma_f32 v[48:49], v[44:45], v[66:67], v[48:49] op_sel:[0,1,0]
	v_pk_fma_f32 v[50:51], v[46:47], v[66:67], v[50:51] op_sel:[0,1,0]
	v_add_f32_dpp v12, v12, v12 row_ror:4 row_mask:0xf bank_mask:0xf bound_ctrl:1
	v_fma_mix_f32 v83, v8, v23, v83 op_sel_hi:[0,1,0]
	v_fma_mix_f32 v83, v9, v23, v83 op_sel:[0,1,0] op_sel_hi:[0,1,0]
	v_add_f32_dpp v12, v12, v12 row_ror:8 row_mask:0xf bank_mask:0xf bound_ctrl:1
	v_pk_fma_f32 v[6:7], v[40:41], v[12:13], v[48:49] op_sel_hi:[1,0,1] neg_lo:[1,0,0] neg_hi:[1,0,0]
	v_pk_fma_f32 v[8:9], v[42:43], v[12:13], v[50:51] op_sel_hi:[1,0,1] neg_lo:[1,0,0] neg_hi:[1,0,0]
	s_waitcnt lgkmcnt(1)
	v_fma_mix_f32 v12, v6, v88, v180 op_sel_hi:[0,1,0]
	v_fma_mix_f32 v12, v7, v88, v12 op_sel:[0,1,0] op_sel_hi:[0,1,0]
	v_fma_mix_f32 v12, v8, v89, v12 op_sel_hi:[0,1,0]
	v_fma_mix_f32 v12, v9, v89, v12 op_sel:[0,1,0] op_sel_hi:[0,1,0]
	v_pk_mul_f32 v[48:49], v[6:7], v[84:85]
	v_pk_mul_f32 v[50:51], v[8:9], v[86:87]
	v_add_f32_dpp v12, v12, v12 row_ror:1 row_mask:0xf bank_mask:0xf bound_ctrl:1
	v_fma_mix_f32 v100, v6, v38, v180 op_sel_hi:[0,1,0]
	v_fma_mix_f32 v100, v7, v38, v100 op_sel:[0,1,0] op_sel_hi:[0,1,0]
	v_add_f32_dpp v12, v12, v12 row_ror:2 row_mask:0xf bank_mask:0xf bound_ctrl:1
	v_pk_fma_f32 v[48:49], v[96:97], v[68:69], v[48:49] op_sel_hi:[1,0,1]
	v_pk_fma_f32 v[50:51], v[98:99], v[68:69], v[50:51] op_sel_hi:[1,0,1]
	v_add_f32_dpp v12, v12, v12 row_ror:4 row_mask:0xf bank_mask:0xf bound_ctrl:1
	v_fma_mix_f32 v100, v8, v39, v100 op_sel_hi:[0,1,0]
	v_fma_mix_f32 v100, v9, v39, v100 op_sel:[0,1,0] op_sel_hi:[0,1,0]
	v_add_f32_dpp v12, v12, v12 row_ror:8 row_mask:0xf bank_mask:0xf bound_ctrl:1
	v_pk_fma_f32 v[6:7], v[92:93], v[12:13], v[48:49] op_sel_hi:[1,0,1] neg_lo:[1,0,0] neg_hi:[1,0,0]
	v_pk_fma_f32 v[8:9], v[94:95], v[12:13], v[50:51] op_sel_hi:[1,0,1] neg_lo:[1,0,0] neg_hi:[1,0,0]
	ds_read_b128 v[20:23], v10 offset:12544
	ds_read_b128 v[16:19], v10 offset:12288
	ds_read_b128 v[28:31], v10 offset:13056
	ds_read_b128 v[24:27], v10 offset:12800
	ds_read_b128 v[36:39], v10 offset:13568
	ds_read_b128 v[32:35], v10 offset:13312
	ds_read_b128 v[44:47], v10 offset:14080
	ds_read_b128 v[40:43], v10 offset:13824
	v_fma_mix_f32 v12, v6, v110, v180 op_sel_hi:[0,1,0]
	v_fma_mix_f32 v12, v7, v110, v12 op_sel:[0,1,0] op_sel_hi:[0,1,0]
	v_fma_mix_f32 v12, v8, v111, v12 op_sel_hi:[0,1,0]
	v_fma_mix_f32 v12, v9, v111, v12 op_sel:[0,1,0] op_sel_hi:[0,1,0]
	v_pk_mul_f32 v[48:49], v[6:7], v[106:107]
	v_pk_mul_f32 v[50:51], v[8:9], v[108:109]
	v_add_f32_dpp v12, v12, v12 row_ror:1 row_mask:0xf bank_mask:0xf bound_ctrl:1
	v_fma_mix_f32 v101, v6, v90, v180 op_sel_hi:[0,1,0]
	v_fma_mix_f32 v101, v7, v90, v101 op_sel:[0,1,0] op_sel_hi:[0,1,0]
	v_add_f32_dpp v12, v12, v12 row_ror:2 row_mask:0xf bank_mask:0xf bound_ctrl:1
	v_pk_fma_f32 v[48:49], v[118:119], v[68:69], v[48:49] op_sel:[0,1,0]
	v_pk_fma_f32 v[50:51], v[120:121], v[68:69], v[50:51] op_sel:[0,1,0]
	v_add_f32_dpp v12, v12, v12 row_ror:4 row_mask:0xf bank_mask:0xf bound_ctrl:1
	v_fma_mix_f32 v101, v8, v91, v101 op_sel_hi:[0,1,0]
	v_fma_mix_f32 v101, v9, v91, v101 op_sel:[0,1,0] op_sel_hi:[0,1,0]
	v_add_f32_dpp v12, v12, v12 row_ror:8 row_mask:0xf bank_mask:0xf bound_ctrl:1
	v_pk_fma_f32 v[6:7], v[114:115], v[12:13], v[48:49] op_sel_hi:[1,0,1] neg_lo:[1,0,0] neg_hi:[1,0,0]
	v_pk_fma_f32 v[8:9], v[116:117], v[12:13], v[50:51] op_sel_hi:[1,0,1] neg_lo:[1,0,0] neg_hi:[1,0,0]
	s_waitcnt lgkmcnt(0)
	v_fma_mix_f32 v12, v6, v20, v180 op_sel_hi:[0,1,0]
	v_fma_mix_f32 v12, v7, v20, v12 op_sel:[0,1,0] op_sel_hi:[0,1,0]
	v_fma_mix_f32 v12, v8, v21, v12 op_sel_hi:[0,1,0]
	v_fma_mix_f32 v12, v9, v21, v12 op_sel:[0,1,0] op_sel_hi:[0,1,0]
	v_pk_mul_f32 v[48:49], v[6:7], v[16:17]
	v_pk_mul_f32 v[50:51], v[8:9], v[18:19]
	v_add_f32_dpp v12, v12, v12 row_ror:1 row_mask:0xf bank_mask:0xf bound_ctrl:1
	v_fma_mix_f32 v102, v6, v112, v180 op_sel_hi:[0,1,0]
	v_fma_mix_f32 v102, v7, v112, v102 op_sel:[0,1,0] op_sel_hi:[0,1,0]
	v_add_f32_dpp v12, v12, v12 row_ror:2 row_mask:0xf bank_mask:0xf bound_ctrl:1
	v_pk_fma_f32 v[48:49], v[28:29], v[70:71], v[48:49] op_sel_hi:[1,0,1]
	v_pk_fma_f32 v[50:51], v[30:31], v[70:71], v[50:51] op_sel_hi:[1,0,1]
	v_add_f32_dpp v12, v12, v12 row_ror:4 row_mask:0xf bank_mask:0xf bound_ctrl:1
	v_fma_mix_f32 v102, v8, v113, v102 op_sel_hi:[0,1,0]
	v_fma_mix_f32 v102, v9, v113, v102 op_sel:[0,1,0] op_sel_hi:[0,1,0]
	v_add_f32_dpp v12, v12, v12 row_ror:8 row_mask:0xf bank_mask:0xf bound_ctrl:1
	v_pk_fma_f32 v[6:7], v[24:25], v[12:13], v[48:49] op_sel_hi:[1,0,1] neg_lo:[1,0,0] neg_hi:[1,0,0]
	v_pk_fma_f32 v[8:9], v[26:27], v[12:13], v[50:51] op_sel_hi:[1,0,1] neg_lo:[1,0,0] neg_hi:[1,0,0]
	ds_read_b128 v[88:91], v10 offset:14592
	ds_read_b128 v[84:87], v10 offset:14336
	ds_read_b128 v[96:99], v10 offset:15104
	ds_read_b128 v[92:95], v10 offset:14848
	ds_read_b128 v[110:113], v10 offset:15616
	ds_read_b128 v[106:109], v10 offset:15360
	ds_read_b128 v[118:121], v10 offset:16128
	ds_read_b128 v[114:117], v10 offset:15872
	ds_read_b128 v[66:69], v11 offset:1024
	v_fma_mix_f32 v12, v6, v36, v180 op_sel_hi:[0,1,0]
	v_fma_mix_f32 v12, v7, v36, v12 op_sel:[0,1,0] op_sel_hi:[0,1,0]
	v_fma_mix_f32 v12, v8, v37, v12 op_sel_hi:[0,1,0]
	v_fma_mix_f32 v12, v9, v37, v12 op_sel:[0,1,0] op_sel_hi:[0,1,0]
	v_pk_mul_f32 v[48:49], v[6:7], v[32:33]
	v_pk_mul_f32 v[50:51], v[8:9], v[34:35]
	v_add_f32_dpp v12, v12, v12 row_ror:1 row_mask:0xf bank_mask:0xf bound_ctrl:1
	v_fma_mix_f32 v103, v6, v22, v180 op_sel_hi:[0,1,0]
	v_fma_mix_f32 v103, v7, v22, v103 op_sel:[0,1,0] op_sel_hi:[0,1,0]
	v_add_f32_dpp v12, v12, v12 row_ror:2 row_mask:0xf bank_mask:0xf bound_ctrl:1
	v_pk_fma_f32 v[48:49], v[44:45], v[70:71], v[48:49] op_sel:[0,1,0]
	v_pk_fma_f32 v[50:51], v[46:47], v[70:71], v[50:51] op_sel:[0,1,0]
	v_add_f32_dpp v12, v12, v12 row_ror:4 row_mask:0xf bank_mask:0xf bound_ctrl:1
	v_fma_mix_f32 v103, v8, v23, v103 op_sel_hi:[0,1,0]
	v_fma_mix_f32 v103, v9, v23, v103 op_sel:[0,1,0] op_sel_hi:[0,1,0]
	v_add_f32_dpp v12, v12, v12 row_ror:8 row_mask:0xf bank_mask:0xf bound_ctrl:1
	v_pk_fma_f32 v[6:7], v[40:41], v[12:13], v[48:49] op_sel_hi:[1,0,1] neg_lo:[1,0,0] neg_hi:[1,0,0]
	v_pk_fma_f32 v[8:9], v[42:43], v[12:13], v[50:51] op_sel_hi:[1,0,1] neg_lo:[1,0,0] neg_hi:[1,0,0]
	s_waitcnt lgkmcnt(1)
	v_fma_mix_f32 v12, v6, v88, v180 op_sel_hi:[0,1,0]
	v_fma_mix_f32 v12, v7, v88, v12 op_sel:[0,1,0] op_sel_hi:[0,1,0]
	v_fma_mix_f32 v12, v8, v89, v12 op_sel_hi:[0,1,0]
	v_fma_mix_f32 v12, v9, v89, v12 op_sel:[0,1,0] op_sel_hi:[0,1,0]
	v_pk_mul_f32 v[48:49], v[6:7], v[84:85]
	v_pk_mul_f32 v[50:51], v[8:9], v[86:87]
	v_add_f32_dpp v12, v12, v12 row_ror:1 row_mask:0xf bank_mask:0xf bound_ctrl:1
	v_fma_mix_f32 v104, v6, v38, v180 op_sel_hi:[0,1,0]
	v_fma_mix_f32 v104, v7, v38, v104 op_sel:[0,1,0] op_sel_hi:[0,1,0]
	v_add_f32_dpp v12, v12, v12 row_ror:2 row_mask:0xf bank_mask:0xf bound_ctrl:1
	v_pk_fma_f32 v[48:49], v[96:97], v[72:73], v[48:49] op_sel_hi:[1,0,1]
	v_pk_fma_f32 v[50:51], v[98:99], v[72:73], v[50:51] op_sel_hi:[1,0,1]
	v_add_f32_dpp v12, v12, v12 row_ror:4 row_mask:0xf bank_mask:0xf bound_ctrl:1
	v_fma_mix_f32 v104, v8, v39, v104 op_sel_hi:[0,1,0]
	v_fma_mix_f32 v104, v9, v39, v104 op_sel:[0,1,0] op_sel_hi:[0,1,0]
	v_add_f32_dpp v12, v12, v12 row_ror:8 row_mask:0xf bank_mask:0xf bound_ctrl:1
	v_pk_fma_f32 v[6:7], v[92:93], v[12:13], v[48:49] op_sel_hi:[1,0,1] neg_lo:[1,0,0] neg_hi:[1,0,0]
	v_pk_fma_f32 v[8:9], v[94:95], v[12:13], v[50:51] op_sel_hi:[1,0,1] neg_lo:[1,0,0] neg_hi:[1,0,0]
	ds_read_b128 v[20:23], v10 offset:16640
	ds_read_b128 v[16:19], v10 offset:16384
	ds_read_b128 v[28:31], v10 offset:17152
	ds_read_b128 v[24:27], v10 offset:16896
	ds_read_b128 v[36:39], v10 offset:17664
	ds_read_b128 v[32:35], v10 offset:17408
	ds_read_b128 v[44:47], v10 offset:18176
	ds_read_b128 v[40:43], v10 offset:17920
	v_fma_mix_f32 v12, v6, v110, v180 op_sel_hi:[0,1,0]
	v_fma_mix_f32 v12, v7, v110, v12 op_sel:[0,1,0] op_sel_hi:[0,1,0]
	v_fma_mix_f32 v12, v8, v111, v12 op_sel_hi:[0,1,0]
	v_fma_mix_f32 v12, v9, v111, v12 op_sel:[0,1,0] op_sel_hi:[0,1,0]
	v_pk_mul_f32 v[48:49], v[6:7], v[106:107]
	v_pk_mul_f32 v[50:51], v[8:9], v[108:109]
	v_add_f32_dpp v12, v12, v12 row_ror:1 row_mask:0xf bank_mask:0xf bound_ctrl:1
	v_fma_mix_f32 v105, v6, v90, v180 op_sel_hi:[0,1,0]
	v_fma_mix_f32 v105, v7, v90, v105 op_sel:[0,1,0] op_sel_hi:[0,1,0]
	v_add_f32_dpp v12, v12, v12 row_ror:2 row_mask:0xf bank_mask:0xf bound_ctrl:1
	v_pk_fma_f32 v[48:49], v[118:119], v[72:73], v[48:49] op_sel:[0,1,0]
	v_pk_fma_f32 v[50:51], v[120:121], v[72:73], v[50:51] op_sel:[0,1,0]
	v_add_f32_dpp v12, v12, v12 row_ror:4 row_mask:0xf bank_mask:0xf bound_ctrl:1
	v_fma_mix_f32 v105, v8, v91, v105 op_sel_hi:[0,1,0]
	v_fma_mix_f32 v105, v9, v91, v105 op_sel:[0,1,0] op_sel_hi:[0,1,0]
	v_add_f32_dpp v12, v12, v12 row_ror:8 row_mask:0xf bank_mask:0xf bound_ctrl:1
	v_pk_fma_f32 v[6:7], v[114:115], v[12:13], v[48:49] op_sel_hi:[1,0,1] neg_lo:[1,0,0] neg_hi:[1,0,0]
	v_pk_fma_f32 v[8:9], v[116:117], v[12:13], v[50:51] op_sel_hi:[1,0,1] neg_lo:[1,0,0] neg_hi:[1,0,0]
	s_waitcnt lgkmcnt(0)
	v_fma_mix_f32 v12, v6, v20, v180 op_sel_hi:[0,1,0]
	v_fma_mix_f32 v12, v7, v20, v12 op_sel:[0,1,0] op_sel_hi:[0,1,0]
	v_fma_mix_f32 v12, v8, v21, v12 op_sel_hi:[0,1,0]
	v_fma_mix_f32 v12, v9, v21, v12 op_sel:[0,1,0] op_sel_hi:[0,1,0]
	v_pk_mul_f32 v[48:49], v[6:7], v[16:17]
	v_pk_mul_f32 v[50:51], v[8:9], v[18:19]
	v_add_f32_dpp v12, v12, v12 row_ror:1 row_mask:0xf bank_mask:0xf bound_ctrl:1
	v_fma_mix_f32 v61, v6, v112, v180 op_sel_hi:[0,1,0]
	v_fma_mix_f32 v61, v7, v112, v61 op_sel:[0,1,0] op_sel_hi:[0,1,0]
	v_add_f32_dpp v12, v12, v12 row_ror:2 row_mask:0xf bank_mask:0xf bound_ctrl:1
	v_pk_fma_f32 v[48:49], v[28:29], v[66:67], v[48:49] op_sel_hi:[1,0,1]
	v_pk_fma_f32 v[50:51], v[30:31], v[66:67], v[50:51] op_sel_hi:[1,0,1]
	v_add_f32_dpp v12, v12, v12 row_ror:4 row_mask:0xf bank_mask:0xf bound_ctrl:1
	v_fma_mix_f32 v61, v8, v113, v61 op_sel_hi:[0,1,0]
	v_fma_mix_f32 v61, v9, v113, v61 op_sel:[0,1,0] op_sel_hi:[0,1,0]
	v_add_f32_dpp v12, v12, v12 row_ror:8 row_mask:0xf bank_mask:0xf bound_ctrl:1
	v_pk_fma_f32 v[6:7], v[24:25], v[12:13], v[48:49] op_sel_hi:[1,0,1] neg_lo:[1,0,0] neg_hi:[1,0,0]
	v_pk_fma_f32 v[8:9], v[26:27], v[12:13], v[50:51] op_sel_hi:[1,0,1] neg_lo:[1,0,0] neg_hi:[1,0,0]
	ds_read_b128 v[88:91], v10 offset:18688
	ds_read_b128 v[84:87], v10 offset:18432
	ds_read_b128 v[96:99], v10 offset:19200
	ds_read_b128 v[92:95], v10 offset:18944
	ds_read_b128 v[110:113], v10 offset:19712
	ds_read_b128 v[106:109], v10 offset:19456
	ds_read_b128 v[118:121], v10 offset:20224
	ds_read_b128 v[114:117], v10 offset:19968
	ds_read_b128 v[70:73], v11 offset:1280
	v_add_f32_dpp v83, v83, v83 row_ror:8 row_mask:0xf bank_mask:0xc
	v_add_f32_dpp v83, v52, v52 row_ror:8 row_mask:0xf bank_mask:0x3
	v_add_f32_dpp v100, v100, v100 row_ror:8 row_mask:0xf bank_mask:0xc
	v_add_f32_dpp v100, v53, v53 row_ror:8 row_mask:0xf bank_mask:0x3
	v_add_f32_dpp v101, v101, v101 row_ror:8 row_mask:0xf bank_mask:0xc
	v_add_f32_dpp v101, v54, v54 row_ror:8 row_mask:0xf bank_mask:0x3
	v_add_f32_dpp v102, v102, v102 row_ror:8 row_mask:0xf bank_mask:0xc
	v_add_f32_dpp v102, v55, v55 row_ror:8 row_mask:0xf bank_mask:0x3
	v_add_f32_dpp v103, v103, v103 row_ror:8 row_mask:0xf bank_mask:0xc
	v_add_f32_dpp v103, v56, v56 row_ror:8 row_mask:0xf bank_mask:0x3
	v_add_f32_dpp v104, v104, v104 row_ror:8 row_mask:0xf bank_mask:0xc
	v_add_f32_dpp v104, v57, v57 row_ror:8 row_mask:0xf bank_mask:0x3
	v_add_f32_dpp v105, v105, v105 row_ror:8 row_mask:0xf bank_mask:0xc
	v_add_f32_dpp v105, v81, v81 row_ror:8 row_mask:0xf bank_mask:0x3
	v_add_f32_dpp v61, v61, v61 row_ror:8 row_mask:0xf bank_mask:0xc
	v_add_f32_dpp v61, v82, v82 row_ror:8 row_mask:0xf bank_mask:0x3
	v_add_f32_dpp v103, v103, v103 row_ror:4 row_mask:0xf bank_mask:0xa
	v_add_f32_dpp v103, v83, v83 row_ror:12 row_mask:0xf bank_mask:0x5
	v_add_f32_dpp v104, v104, v104 row_ror:4 row_mask:0xf bank_mask:0xa
	v_add_f32_dpp v104, v100, v100 row_ror:12 row_mask:0xf bank_mask:0x5
	v_add_f32_dpp v105, v105, v105 row_ror:4 row_mask:0xf bank_mask:0xa
	v_add_f32_dpp v105, v101, v101 row_ror:12 row_mask:0xf bank_mask:0x5
	v_add_f32_dpp v61, v61, v61 row_ror:4 row_mask:0xf bank_mask:0xa
	v_add_f32_dpp v61, v102, v102 row_ror:12 row_mask:0xf bank_mask:0x5
	v_cndmask_b32_e64 v62, v105, v103, s[38:39]
	v_cndmask_b32_e64 v63, v103, v105, s[38:39]
	v_cndmask_b32_e64 v64, v61, v104, s[38:39]
	v_cndmask_b32_e64 v65, v104, v61, s[38:39]
	v_add_f32_dpp v62, v63, v62 quad_perm:[2,3,0,1] row_mask:0xf bank_mask:0xf bound_ctrl:1
	s_nop 0
	v_add_f32_dpp v63, v65, v64 quad_perm:[2,3,0,1] row_mask:0xf bank_mask:0xf bound_ctrl:1
	v_cndmask_b32_e64 v65, v63, v62, s[40:41]
	v_cndmask_b32_e64 v62, v62, v63, s[40:41]
	s_nop 1
	v_add_f32_dpp v62, v62, v65 quad_perm:[1,0,3,2] row_mask:0xf bank_mask:0xf bound_ctrl:1
	v_cvt_pk_bf16_f32 v62, v62, v62
	global_store_short v[2:3], v62, off
	v_lshl_add_u64 v[2:3], v[2:3], 0, s[84:85]
	v_fma_mix_f32 v12, v6, v36, v180 op_sel_hi:[0,1,0]
	v_fma_mix_f32 v12, v7, v36, v12 op_sel:[0,1,0] op_sel_hi:[0,1,0]
	v_fma_mix_f32 v12, v8, v37, v12 op_sel_hi:[0,1,0]
	v_fma_mix_f32 v12, v9, v37, v12 op_sel:[0,1,0] op_sel_hi:[0,1,0]
	v_pk_mul_f32 v[48:49], v[6:7], v[32:33]
	v_pk_mul_f32 v[50:51], v[8:9], v[34:35]
	v_add_f32_dpp v12, v12, v12 row_ror:1 row_mask:0xf bank_mask:0xf bound_ctrl:1
	v_fma_mix_f32 v52, v6, v22, v180 op_sel_hi:[0,1,0]
	v_fma_mix_f32 v52, v7, v22, v52 op_sel:[0,1,0] op_sel_hi:[0,1,0]
	v_add_f32_dpp v12, v12, v12 row_ror:2 row_mask:0xf bank_mask:0xf bound_ctrl:1
	v_pk_fma_f32 v[48:49], v[44:45], v[66:67], v[48:49] op_sel:[0,1,0]
	v_pk_fma_f32 v[50:51], v[46:47], v[66:67], v[50:51] op_sel:[0,1,0]
	v_add_f32_dpp v12, v12, v12 row_ror:4 row_mask:0xf bank_mask:0xf bound_ctrl:1
	v_fma_mix_f32 v52, v8, v23, v52 op_sel_hi:[0,1,0]
	v_fma_mix_f32 v52, v9, v23, v52 op_sel:[0,1,0] op_sel_hi:[0,1,0]
	v_add_f32_dpp v12, v12, v12 row_ror:8 row_mask:0xf bank_mask:0xf bound_ctrl:1
	v_pk_fma_f32 v[6:7], v[40:41], v[12:13], v[48:49] op_sel_hi:[1,0,1] neg_lo:[1,0,0] neg_hi:[1,0,0]
	v_pk_fma_f32 v[8:9], v[42:43], v[12:13], v[50:51] op_sel_hi:[1,0,1] neg_lo:[1,0,0] neg_hi:[1,0,0]
	s_waitcnt lgkmcnt(1)
	v_fma_mix_f32 v12, v6, v88, v180 op_sel_hi:[0,1,0]
	v_fma_mix_f32 v12, v7, v88, v12 op_sel:[0,1,0] op_sel_hi:[0,1,0]
	v_fma_mix_f32 v12, v8, v89, v12 op_sel_hi:[0,1,0]
	v_fma_mix_f32 v12, v9, v89, v12 op_sel:[0,1,0] op_sel_hi:[0,1,0]
	v_pk_mul_f32 v[48:49], v[6:7], v[84:85]
	v_pk_mul_f32 v[50:51], v[8:9], v[86:87]
	v_add_f32_dpp v12, v12, v12 row_ror:1 row_mask:0xf bank_mask:0xf bound_ctrl:1
	v_fma_mix_f32 v53, v6, v38, v180 op_sel_hi:[0,1,0]
	v_fma_mix_f32 v53, v7, v38, v53 op_sel:[0,1,0] op_sel_hi:[0,1,0]
	v_add_f32_dpp v12, v12, v12 row_ror:2 row_mask:0xf bank_mask:0xf bound_ctrl:1
	v_pk_fma_f32 v[48:49], v[96:97], v[68:69], v[48:49] op_sel_hi:[1,0,1]
	v_pk_fma_f32 v[50:51], v[98:99], v[68:69], v[50:51] op_sel_hi:[1,0,1]
	v_add_f32_dpp v12, v12, v12 row_ror:4 row_mask:0xf bank_mask:0xf bound_ctrl:1
	v_fma_mix_f32 v53, v8, v39, v53 op_sel_hi:[0,1,0]
	v_fma_mix_f32 v53, v9, v39, v53 op_sel:[0,1,0] op_sel_hi:[0,1,0]
	v_add_f32_dpp v12, v12, v12 row_ror:8 row_mask:0xf bank_mask:0xf bound_ctrl:1
	v_pk_fma_f32 v[6:7], v[92:93], v[12:13], v[48:49] op_sel_hi:[1,0,1] neg_lo:[1,0,0] neg_hi:[1,0,0]
	v_pk_fma_f32 v[8:9], v[94:95], v[12:13], v[50:51] op_sel_hi:[1,0,1] neg_lo:[1,0,0] neg_hi:[1,0,0]
	ds_read_b128 v[20:23], v10 offset:20736
	ds_read_b128 v[16:19], v10 offset:20480
	ds_read_b128 v[28:31], v10 offset:21248
	ds_read_b128 v[24:27], v10 offset:20992
	ds_read_b128 v[36:39], v10 offset:21760
	ds_read_b128 v[32:35], v10 offset:21504
	ds_read_b128 v[44:47], v10 offset:22272
	ds_read_b128 v[40:43], v10 offset:22016
	v_fma_mix_f32 v12, v6, v110, v180 op_sel_hi:[0,1,0]
	v_fma_mix_f32 v12, v7, v110, v12 op_sel:[0,1,0] op_sel_hi:[0,1,0]
	v_fma_mix_f32 v12, v8, v111, v12 op_sel_hi:[0,1,0]
	v_fma_mix_f32 v12, v9, v111, v12 op_sel:[0,1,0] op_sel_hi:[0,1,0]
	v_pk_mul_f32 v[48:49], v[6:7], v[106:107]
	v_pk_mul_f32 v[50:51], v[8:9], v[108:109]
	v_add_f32_dpp v12, v12, v12 row_ror:1 row_mask:0xf bank_mask:0xf bound_ctrl:1
	v_fma_mix_f32 v54, v6, v90, v180 op_sel_hi:[0,1,0]
	v_fma_mix_f32 v54, v7, v90, v54 op_sel:[0,1,0] op_sel_hi:[0,1,0]
	v_add_f32_dpp v12, v12, v12 row_ror:2 row_mask:0xf bank_mask:0xf bound_ctrl:1
	v_pk_fma_f32 v[48:49], v[118:119], v[68:69], v[48:49] op_sel:[0,1,0]
	v_pk_fma_f32 v[50:51], v[120:121], v[68:69], v[50:51] op_sel:[0,1,0]
	v_add_f32_dpp v12, v12, v12 row_ror:4 row_mask:0xf bank_mask:0xf bound_ctrl:1
	v_fma_mix_f32 v54, v8, v91, v54 op_sel_hi:[0,1,0]
	v_fma_mix_f32 v54, v9, v91, v54 op_sel:[0,1,0] op_sel_hi:[0,1,0]
	v_add_f32_dpp v12, v12, v12 row_ror:8 row_mask:0xf bank_mask:0xf bound_ctrl:1
	v_pk_fma_f32 v[6:7], v[114:115], v[12:13], v[48:49] op_sel_hi:[1,0,1] neg_lo:[1,0,0] neg_hi:[1,0,0]
	v_pk_fma_f32 v[8:9], v[116:117], v[12:13], v[50:51] op_sel_hi:[1,0,1] neg_lo:[1,0,0] neg_hi:[1,0,0]
	s_waitcnt lgkmcnt(0)
	v_fma_mix_f32 v12, v6, v20, v180 op_sel_hi:[0,1,0]
	v_fma_mix_f32 v12, v7, v20, v12 op_sel:[0,1,0] op_sel_hi:[0,1,0]
	v_fma_mix_f32 v12, v8, v21, v12 op_sel_hi:[0,1,0]
	v_fma_mix_f32 v12, v9, v21, v12 op_sel:[0,1,0] op_sel_hi:[0,1,0]
	v_pk_mul_f32 v[48:49], v[6:7], v[16:17]
	v_pk_mul_f32 v[50:51], v[8:9], v[18:19]
	v_add_f32_dpp v12, v12, v12 row_ror:1 row_mask:0xf bank_mask:0xf bound_ctrl:1
	v_fma_mix_f32 v55, v6, v112, v180 op_sel_hi:[0,1,0]
	v_fma_mix_f32 v55, v7, v112, v55 op_sel:[0,1,0] op_sel_hi:[0,1,0]
	v_add_f32_dpp v12, v12, v12 row_ror:2 row_mask:0xf bank_mask:0xf bound_ctrl:1
	v_pk_fma_f32 v[48:49], v[28:29], v[70:71], v[48:49] op_sel_hi:[1,0,1]
	v_pk_fma_f32 v[50:51], v[30:31], v[70:71], v[50:51] op_sel_hi:[1,0,1]
	v_add_f32_dpp v12, v12, v12 row_ror:4 row_mask:0xf bank_mask:0xf bound_ctrl:1
	v_fma_mix_f32 v55, v8, v113, v55 op_sel_hi:[0,1,0]
	v_fma_mix_f32 v55, v9, v113, v55 op_sel:[0,1,0] op_sel_hi:[0,1,0]
	v_add_f32_dpp v12, v12, v12 row_ror:8 row_mask:0xf bank_mask:0xf bound_ctrl:1
	v_pk_fma_f32 v[6:7], v[24:25], v[12:13], v[48:49] op_sel_hi:[1,0,1] neg_lo:[1,0,0] neg_hi:[1,0,0]
	v_pk_fma_f32 v[8:9], v[26:27], v[12:13], v[50:51] op_sel_hi:[1,0,1] neg_lo:[1,0,0] neg_hi:[1,0,0]
	ds_read_b128 v[88:91], v10 offset:22784
	ds_read_b128 v[84:87], v10 offset:22528
	ds_read_b128 v[96:99], v10 offset:23296
	ds_read_b128 v[92:95], v10 offset:23040
	ds_read_b128 v[110:113], v10 offset:23808
	ds_read_b128 v[106:109], v10 offset:23552
	ds_read_b128 v[118:121], v10 offset:24320
	ds_read_b128 v[114:117], v10 offset:24064
	ds_read_b128 v[66:69], v11 offset:1536
	v_fma_mix_f32 v12, v6, v36, v180 op_sel_hi:[0,1,0]
	v_fma_mix_f32 v12, v7, v36, v12 op_sel:[0,1,0] op_sel_hi:[0,1,0]
	v_fma_mix_f32 v12, v8, v37, v12 op_sel_hi:[0,1,0]
	v_fma_mix_f32 v12, v9, v37, v12 op_sel:[0,1,0] op_sel_hi:[0,1,0]
	v_pk_mul_f32 v[48:49], v[6:7], v[32:33]
	v_pk_mul_f32 v[50:51], v[8:9], v[34:35]
	v_add_f32_dpp v12, v12, v12 row_ror:1 row_mask:0xf bank_mask:0xf bound_ctrl:1
	v_fma_mix_f32 v56, v6, v22, v180 op_sel_hi:[0,1,0]
	v_fma_mix_f32 v56, v7, v22, v56 op_sel:[0,1,0] op_sel_hi:[0,1,0]
	v_add_f32_dpp v12, v12, v12 row_ror:2 row_mask:0xf bank_mask:0xf bound_ctrl:1
	v_pk_fma_f32 v[48:49], v[44:45], v[70:71], v[48:49] op_sel:[0,1,0]
	v_pk_fma_f32 v[50:51], v[46:47], v[70:71], v[50:51] op_sel:[0,1,0]
	v_add_f32_dpp v12, v12, v12 row_ror:4 row_mask:0xf bank_mask:0xf bound_ctrl:1
	v_fma_mix_f32 v56, v8, v23, v56 op_sel_hi:[0,1,0]
	v_fma_mix_f32 v56, v9, v23, v56 op_sel:[0,1,0] op_sel_hi:[0,1,0]
	v_add_f32_dpp v12, v12, v12 row_ror:8 row_mask:0xf bank_mask:0xf bound_ctrl:1
	v_pk_fma_f32 v[6:7], v[40:41], v[12:13], v[48:49] op_sel_hi:[1,0,1] neg_lo:[1,0,0] neg_hi:[1,0,0]
	v_pk_fma_f32 v[8:9], v[42:43], v[12:13], v[50:51] op_sel_hi:[1,0,1] neg_lo:[1,0,0] neg_hi:[1,0,0]
	s_waitcnt lgkmcnt(1)
	v_fma_mix_f32 v12, v6, v88, v180 op_sel_hi:[0,1,0]
	v_fma_mix_f32 v12, v7, v88, v12 op_sel:[0,1,0] op_sel_hi:[0,1,0]
	v_fma_mix_f32 v12, v8, v89, v12 op_sel_hi:[0,1,0]
	v_fma_mix_f32 v12, v9, v89, v12 op_sel:[0,1,0] op_sel_hi:[0,1,0]
	v_pk_mul_f32 v[48:49], v[6:7], v[84:85]
	v_pk_mul_f32 v[50:51], v[8:9], v[86:87]
	v_add_f32_dpp v12, v12, v12 row_ror:1 row_mask:0xf bank_mask:0xf bound_ctrl:1
	v_fma_mix_f32 v57, v6, v38, v180 op_sel_hi:[0,1,0]
	v_fma_mix_f32 v57, v7, v38, v57 op_sel:[0,1,0] op_sel_hi:[0,1,0]
	v_add_f32_dpp v12, v12, v12 row_ror:2 row_mask:0xf bank_mask:0xf bound_ctrl:1
	v_pk_fma_f32 v[48:49], v[96:97], v[72:73], v[48:49] op_sel_hi:[1,0,1]
	v_pk_fma_f32 v[50:51], v[98:99], v[72:73], v[50:51] op_sel_hi:[1,0,1]
	v_add_f32_dpp v12, v12, v12 row_ror:4 row_mask:0xf bank_mask:0xf bound_ctrl:1
	v_fma_mix_f32 v57, v8, v39, v57 op_sel_hi:[0,1,0]
	v_fma_mix_f32 v57, v9, v39, v57 op_sel:[0,1,0] op_sel_hi:[0,1,0]
	v_add_f32_dpp v12, v12, v12 row_ror:8 row_mask:0xf bank_mask:0xf bound_ctrl:1
	v_pk_fma_f32 v[6:7], v[92:93], v[12:13], v[48:49] op_sel_hi:[1,0,1] neg_lo:[1,0,0] neg_hi:[1,0,0]
	v_pk_fma_f32 v[8:9], v[94:95], v[12:13], v[50:51] op_sel_hi:[1,0,1] neg_lo:[1,0,0] neg_hi:[1,0,0]
	ds_read_b128 v[20:23], v10 offset:24832
	ds_read_b128 v[16:19], v10 offset:24576
	ds_read_b128 v[28:31], v10 offset:25344
	ds_read_b128 v[24:27], v10 offset:25088
	ds_read_b128 v[36:39], v10 offset:25856
	ds_read_b128 v[32:35], v10 offset:25600
	ds_read_b128 v[44:47], v10 offset:26368
	ds_read_b128 v[40:43], v10 offset:26112
	v_fma_mix_f32 v12, v6, v110, v180 op_sel_hi:[0,1,0]
	v_fma_mix_f32 v12, v7, v110, v12 op_sel:[0,1,0] op_sel_hi:[0,1,0]
	v_fma_mix_f32 v12, v8, v111, v12 op_sel_hi:[0,1,0]
	v_fma_mix_f32 v12, v9, v111, v12 op_sel:[0,1,0] op_sel_hi:[0,1,0]
	v_pk_mul_f32 v[48:49], v[6:7], v[106:107]
	v_pk_mul_f32 v[50:51], v[8:9], v[108:109]
	v_add_f32_dpp v12, v12, v12 row_ror:1 row_mask:0xf bank_mask:0xf bound_ctrl:1
	v_fma_mix_f32 v81, v6, v90, v180 op_sel_hi:[0,1,0]
	v_fma_mix_f32 v81, v7, v90, v81 op_sel:[0,1,0] op_sel_hi:[0,1,0]
	v_add_f32_dpp v12, v12, v12 row_ror:2 row_mask:0xf bank_mask:0xf bound_ctrl:1
	v_pk_fma_f32 v[48:49], v[118:119], v[72:73], v[48:49] op_sel:[0,1,0]
	v_pk_fma_f32 v[50:51], v[120:121], v[72:73], v[50:51] op_sel:[0,1,0]
	v_add_f32_dpp v12, v12, v12 row_ror:4 row_mask:0xf bank_mask:0xf bound_ctrl:1
	v_fma_mix_f32 v81, v8, v91, v81 op_sel_hi:[0,1,0]
	v_fma_mix_f32 v81, v9, v91, v81 op_sel:[0,1,0] op_sel_hi:[0,1,0]
	v_add_f32_dpp v12, v12, v12 row_ror:8 row_mask:0xf bank_mask:0xf bound_ctrl:1
	v_pk_fma_f32 v[6:7], v[114:115], v[12:13], v[48:49] op_sel_hi:[1,0,1] neg_lo:[1,0,0] neg_hi:[1,0,0]
	v_pk_fma_f32 v[8:9], v[116:117], v[12:13], v[50:51] op_sel_hi:[1,0,1] neg_lo:[1,0,0] neg_hi:[1,0,0]
	s_waitcnt lgkmcnt(0)
	v_fma_mix_f32 v12, v6, v20, v180 op_sel_hi:[0,1,0]
	v_fma_mix_f32 v12, v7, v20, v12 op_sel:[0,1,0] op_sel_hi:[0,1,0]
	v_fma_mix_f32 v12, v8, v21, v12 op_sel_hi:[0,1,0]
	v_fma_mix_f32 v12, v9, v21, v12 op_sel:[0,1,0] op_sel_hi:[0,1,0]
	v_pk_mul_f32 v[48:49], v[6:7], v[16:17]
	v_pk_mul_f32 v[50:51], v[8:9], v[18:19]
	v_add_f32_dpp v12, v12, v12 row_ror:1 row_mask:0xf bank_mask:0xf bound_ctrl:1
	v_fma_mix_f32 v82, v6, v112, v180 op_sel_hi:[0,1,0]
	v_fma_mix_f32 v82, v7, v112, v82 op_sel:[0,1,0] op_sel_hi:[0,1,0]
	v_add_f32_dpp v12, v12, v12 row_ror:2 row_mask:0xf bank_mask:0xf bound_ctrl:1
	v_pk_fma_f32 v[48:49], v[28:29], v[66:67], v[48:49] op_sel_hi:[1,0,1]
	v_pk_fma_f32 v[50:51], v[30:31], v[66:67], v[50:51] op_sel_hi:[1,0,1]
	v_add_f32_dpp v12, v12, v12 row_ror:4 row_mask:0xf bank_mask:0xf bound_ctrl:1
	v_fma_mix_f32 v82, v8, v113, v82 op_sel_hi:[0,1,0]
	v_fma_mix_f32 v82, v9, v113, v82 op_sel:[0,1,0] op_sel_hi:[0,1,0]
	v_add_f32_dpp v12, v12, v12 row_ror:8 row_mask:0xf bank_mask:0xf bound_ctrl:1
	v_pk_fma_f32 v[6:7], v[24:25], v[12:13], v[48:49] op_sel_hi:[1,0,1] neg_lo:[1,0,0] neg_hi:[1,0,0]
	v_pk_fma_f32 v[8:9], v[26:27], v[12:13], v[50:51] op_sel_hi:[1,0,1] neg_lo:[1,0,0] neg_hi:[1,0,0]
	ds_read_b128 v[88:91], v10 offset:26880
	ds_read_b128 v[84:87], v10 offset:26624
	ds_read_b128 v[96:99], v10 offset:27392
	ds_read_b128 v[92:95], v10 offset:27136
	ds_read_b128 v[110:113], v10 offset:27904
	ds_read_b128 v[106:109], v10 offset:27648
	ds_read_b128 v[118:121], v10 offset:28416
	ds_read_b128 v[114:117], v10 offset:28160
	ds_read_b128 v[70:73], v11 offset:1792
	v_fma_mix_f32 v12, v6, v36, v180 op_sel_hi:[0,1,0]
	v_fma_mix_f32 v12, v7, v36, v12 op_sel:[0,1,0] op_sel_hi:[0,1,0]
	v_fma_mix_f32 v12, v8, v37, v12 op_sel_hi:[0,1,0]
	v_fma_mix_f32 v12, v9, v37, v12 op_sel:[0,1,0] op_sel_hi:[0,1,0]
	v_pk_mul_f32 v[48:49], v[6:7], v[32:33]
	v_pk_mul_f32 v[50:51], v[8:9], v[34:35]
	v_add_f32_dpp v12, v12, v12 row_ror:1 row_mask:0xf bank_mask:0xf bound_ctrl:1
	v_fma_mix_f32 v83, v6, v22, v180 op_sel_hi:[0,1,0]
	v_fma_mix_f32 v83, v7, v22, v83 op_sel:[0,1,0] op_sel_hi:[0,1,0]
	v_add_f32_dpp v12, v12, v12 row_ror:2 row_mask:0xf bank_mask:0xf bound_ctrl:1
	v_pk_fma_f32 v[48:49], v[44:45], v[66:67], v[48:49] op_sel:[0,1,0]
	v_pk_fma_f32 v[50:51], v[46:47], v[66:67], v[50:51] op_sel:[0,1,0]
	v_add_f32_dpp v12, v12, v12 row_ror:4 row_mask:0xf bank_mask:0xf bound_ctrl:1
	v_fma_mix_f32 v83, v8, v23, v83 op_sel_hi:[0,1,0]
	v_fma_mix_f32 v83, v9, v23, v83 op_sel:[0,1,0] op_sel_hi:[0,1,0]
	v_add_f32_dpp v12, v12, v12 row_ror:8 row_mask:0xf bank_mask:0xf bound_ctrl:1
	v_pk_fma_f32 v[6:7], v[40:41], v[12:13], v[48:49] op_sel_hi:[1,0,1] neg_lo:[1,0,0] neg_hi:[1,0,0]
	v_pk_fma_f32 v[8:9], v[42:43], v[12:13], v[50:51] op_sel_hi:[1,0,1] neg_lo:[1,0,0] neg_hi:[1,0,0]
	s_waitcnt lgkmcnt(1)
	v_fma_mix_f32 v12, v6, v88, v180 op_sel_hi:[0,1,0]
	v_fma_mix_f32 v12, v7, v88, v12 op_sel:[0,1,0] op_sel_hi:[0,1,0]
	v_fma_mix_f32 v12, v8, v89, v12 op_sel_hi:[0,1,0]
	v_fma_mix_f32 v12, v9, v89, v12 op_sel:[0,1,0] op_sel_hi:[0,1,0]
	v_pk_mul_f32 v[48:49], v[6:7], v[84:85]
	v_pk_mul_f32 v[50:51], v[8:9], v[86:87]
	v_add_f32_dpp v12, v12, v12 row_ror:1 row_mask:0xf bank_mask:0xf bound_ctrl:1
	v_fma_mix_f32 v100, v6, v38, v180 op_sel_hi:[0,1,0]
	v_fma_mix_f32 v100, v7, v38, v100 op_sel:[0,1,0] op_sel_hi:[0,1,0]
	v_add_f32_dpp v12, v12, v12 row_ror:2 row_mask:0xf bank_mask:0xf bound_ctrl:1
	v_pk_fma_f32 v[48:49], v[96:97], v[68:69], v[48:49] op_sel_hi:[1,0,1]
	v_pk_fma_f32 v[50:51], v[98:99], v[68:69], v[50:51] op_sel_hi:[1,0,1]
	v_add_f32_dpp v12, v12, v12 row_ror:4 row_mask:0xf bank_mask:0xf bound_ctrl:1
	v_fma_mix_f32 v100, v8, v39, v100 op_sel_hi:[0,1,0]
	v_fma_mix_f32 v100, v9, v39, v100 op_sel:[0,1,0] op_sel_hi:[0,1,0]
	v_add_f32_dpp v12, v12, v12 row_ror:8 row_mask:0xf bank_mask:0xf bound_ctrl:1
	v_pk_fma_f32 v[6:7], v[92:93], v[12:13], v[48:49] op_sel_hi:[1,0,1] neg_lo:[1,0,0] neg_hi:[1,0,0]
	v_pk_fma_f32 v[8:9], v[94:95], v[12:13], v[50:51] op_sel_hi:[1,0,1] neg_lo:[1,0,0] neg_hi:[1,0,0]
	ds_read_b128 v[20:23], v10 offset:28928
	ds_read_b128 v[16:19], v10 offset:28672
	ds_read_b128 v[28:31], v10 offset:29440
	ds_read_b128 v[24:27], v10 offset:29184
	ds_read_b128 v[36:39], v10 offset:29952
	ds_read_b128 v[32:35], v10 offset:29696
	ds_read_b128 v[44:47], v10 offset:30464
	ds_read_b128 v[40:43], v10 offset:30208
	v_fma_mix_f32 v12, v6, v110, v180 op_sel_hi:[0,1,0]
	v_fma_mix_f32 v12, v7, v110, v12 op_sel:[0,1,0] op_sel_hi:[0,1,0]
	v_fma_mix_f32 v12, v8, v111, v12 op_sel_hi:[0,1,0]
	v_fma_mix_f32 v12, v9, v111, v12 op_sel:[0,1,0] op_sel_hi:[0,1,0]
	v_pk_mul_f32 v[48:49], v[6:7], v[106:107]
	v_pk_mul_f32 v[50:51], v[8:9], v[108:109]
	v_add_f32_dpp v12, v12, v12 row_ror:1 row_mask:0xf bank_mask:0xf bound_ctrl:1
	v_fma_mix_f32 v101, v6, v90, v180 op_sel_hi:[0,1,0]
	v_fma_mix_f32 v101, v7, v90, v101 op_sel:[0,1,0] op_sel_hi:[0,1,0]
	v_add_f32_dpp v12, v12, v12 row_ror:2 row_mask:0xf bank_mask:0xf bound_ctrl:1
	v_pk_fma_f32 v[48:49], v[118:119], v[68:69], v[48:49] op_sel:[0,1,0]
	v_pk_fma_f32 v[50:51], v[120:121], v[68:69], v[50:51] op_sel:[0,1,0]
	v_add_f32_dpp v12, v12, v12 row_ror:4 row_mask:0xf bank_mask:0xf bound_ctrl:1
	v_fma_mix_f32 v101, v8, v91, v101 op_sel_hi:[0,1,0]
	v_fma_mix_f32 v101, v9, v91, v101 op_sel:[0,1,0] op_sel_hi:[0,1,0]
	v_add_f32_dpp v12, v12, v12 row_ror:8 row_mask:0xf bank_mask:0xf bound_ctrl:1
	v_pk_fma_f32 v[6:7], v[114:115], v[12:13], v[48:49] op_sel_hi:[1,0,1] neg_lo:[1,0,0] neg_hi:[1,0,0]
	v_pk_fma_f32 v[8:9], v[116:117], v[12:13], v[50:51] op_sel_hi:[1,0,1] neg_lo:[1,0,0] neg_hi:[1,0,0]
	s_waitcnt lgkmcnt(0)
	v_fma_mix_f32 v12, v6, v20, v180 op_sel_hi:[0,1,0]
	v_fma_mix_f32 v12, v7, v20, v12 op_sel:[0,1,0] op_sel_hi:[0,1,0]
	v_fma_mix_f32 v12, v8, v21, v12 op_sel_hi:[0,1,0]
	v_fma_mix_f32 v12, v9, v21, v12 op_sel:[0,1,0] op_sel_hi:[0,1,0]
	v_pk_mul_f32 v[48:49], v[6:7], v[16:17]
	v_pk_mul_f32 v[50:51], v[8:9], v[18:19]
	v_add_f32_dpp v12, v12, v12 row_ror:1 row_mask:0xf bank_mask:0xf bound_ctrl:1
	v_fma_mix_f32 v102, v6, v112, v180 op_sel_hi:[0,1,0]
	v_fma_mix_f32 v102, v7, v112, v102 op_sel:[0,1,0] op_sel_hi:[0,1,0]
	v_add_f32_dpp v12, v12, v12 row_ror:2 row_mask:0xf bank_mask:0xf bound_ctrl:1
	v_pk_fma_f32 v[48:49], v[28:29], v[70:71], v[48:49] op_sel_hi:[1,0,1]
	v_pk_fma_f32 v[50:51], v[30:31], v[70:71], v[50:51] op_sel_hi:[1,0,1]
	v_add_f32_dpp v12, v12, v12 row_ror:4 row_mask:0xf bank_mask:0xf bound_ctrl:1
	v_fma_mix_f32 v102, v8, v113, v102 op_sel_hi:[0,1,0]
	v_fma_mix_f32 v102, v9, v113, v102 op_sel:[0,1,0] op_sel_hi:[0,1,0]
	v_add_f32_dpp v12, v12, v12 row_ror:8 row_mask:0xf bank_mask:0xf bound_ctrl:1
	v_pk_fma_f32 v[6:7], v[24:25], v[12:13], v[48:49] op_sel_hi:[1,0,1] neg_lo:[1,0,0] neg_hi:[1,0,0]
	v_pk_fma_f32 v[8:9], v[26:27], v[12:13], v[50:51] op_sel_hi:[1,0,1] neg_lo:[1,0,0] neg_hi:[1,0,0]
	ds_read_b128 v[88:91], v10 offset:30976
	ds_read_b128 v[84:87], v10 offset:30720
	ds_read_b128 v[96:99], v10 offset:31488
	ds_read_b128 v[92:95], v10 offset:31232
	ds_read_b128 v[110:113], v10 offset:32000
	ds_read_b128 v[106:109], v10 offset:31744
	ds_read_b128 v[118:121], v10 offset:32512
	ds_read_b128 v[114:117], v10 offset:32256
	ds_read_b128 v[66:69], v11 offset:2048
	v_fma_mix_f32 v12, v6, v36, v180 op_sel_hi:[0,1,0]
	v_fma_mix_f32 v12, v7, v36, v12 op_sel:[0,1,0] op_sel_hi:[0,1,0]
	v_fma_mix_f32 v12, v8, v37, v12 op_sel_hi:[0,1,0]
	v_fma_mix_f32 v12, v9, v37, v12 op_sel:[0,1,0] op_sel_hi:[0,1,0]
	v_pk_mul_f32 v[48:49], v[6:7], v[32:33]
	v_pk_mul_f32 v[50:51], v[8:9], v[34:35]
	v_add_f32_dpp v12, v12, v12 row_ror:1 row_mask:0xf bank_mask:0xf bound_ctrl:1
	v_fma_mix_f32 v103, v6, v22, v180 op_sel_hi:[0,1,0]
	v_fma_mix_f32 v103, v7, v22, v103 op_sel:[0,1,0] op_sel_hi:[0,1,0]
	v_add_f32_dpp v12, v12, v12 row_ror:2 row_mask:0xf bank_mask:0xf bound_ctrl:1
	v_pk_fma_f32 v[48:49], v[44:45], v[70:71], v[48:49] op_sel:[0,1,0]
	v_pk_fma_f32 v[50:51], v[46:47], v[70:71], v[50:51] op_sel:[0,1,0]
	v_add_f32_dpp v12, v12, v12 row_ror:4 row_mask:0xf bank_mask:0xf bound_ctrl:1
	v_fma_mix_f32 v103, v8, v23, v103 op_sel_hi:[0,1,0]
	v_fma_mix_f32 v103, v9, v23, v103 op_sel:[0,1,0] op_sel_hi:[0,1,0]
	v_add_f32_dpp v12, v12, v12 row_ror:8 row_mask:0xf bank_mask:0xf bound_ctrl:1
	v_pk_fma_f32 v[6:7], v[40:41], v[12:13], v[48:49] op_sel_hi:[1,0,1] neg_lo:[1,0,0] neg_hi:[1,0,0]
	v_pk_fma_f32 v[8:9], v[42:43], v[12:13], v[50:51] op_sel_hi:[1,0,1] neg_lo:[1,0,0] neg_hi:[1,0,0]
	s_waitcnt lgkmcnt(1)
	v_fma_mix_f32 v12, v6, v88, v180 op_sel_hi:[0,1,0]
	v_fma_mix_f32 v12, v7, v88, v12 op_sel:[0,1,0] op_sel_hi:[0,1,0]
	v_fma_mix_f32 v12, v8, v89, v12 op_sel_hi:[0,1,0]
	v_fma_mix_f32 v12, v9, v89, v12 op_sel:[0,1,0] op_sel_hi:[0,1,0]
	v_pk_mul_f32 v[48:49], v[6:7], v[84:85]
	v_pk_mul_f32 v[50:51], v[8:9], v[86:87]
	v_add_f32_dpp v12, v12, v12 row_ror:1 row_mask:0xf bank_mask:0xf bound_ctrl:1
	v_fma_mix_f32 v104, v6, v38, v180 op_sel_hi:[0,1,0]
	v_fma_mix_f32 v104, v7, v38, v104 op_sel:[0,1,0] op_sel_hi:[0,1,0]
	v_add_f32_dpp v12, v12, v12 row_ror:2 row_mask:0xf bank_mask:0xf bound_ctrl:1
	v_pk_fma_f32 v[48:49], v[96:97], v[72:73], v[48:49] op_sel_hi:[1,0,1]
	v_pk_fma_f32 v[50:51], v[98:99], v[72:73], v[50:51] op_sel_hi:[1,0,1]
	v_add_f32_dpp v12, v12, v12 row_ror:4 row_mask:0xf bank_mask:0xf bound_ctrl:1
	v_fma_mix_f32 v104, v8, v39, v104 op_sel_hi:[0,1,0]
	v_fma_mix_f32 v104, v9, v39, v104 op_sel:[0,1,0] op_sel_hi:[0,1,0]
	v_add_f32_dpp v12, v12, v12 row_ror:8 row_mask:0xf bank_mask:0xf bound_ctrl:1
	v_pk_fma_f32 v[6:7], v[92:93], v[12:13], v[48:49] op_sel_hi:[1,0,1] neg_lo:[1,0,0] neg_hi:[1,0,0]
	v_pk_fma_f32 v[8:9], v[94:95], v[12:13], v[50:51] op_sel_hi:[1,0,1] neg_lo:[1,0,0] neg_hi:[1,0,0]
	ds_read_b128 v[20:23], v10 offset:33024
	ds_read_b128 v[16:19], v10 offset:32768
	ds_read_b128 v[28:31], v10 offset:33536
	ds_read_b128 v[24:27], v10 offset:33280
	ds_read_b128 v[36:39], v10 offset:34048
	ds_read_b128 v[32:35], v10 offset:33792
	ds_read_b128 v[44:47], v10 offset:34560
	ds_read_b128 v[40:43], v10 offset:34304
	v_fma_mix_f32 v12, v6, v110, v180 op_sel_hi:[0,1,0]
	v_fma_mix_f32 v12, v7, v110, v12 op_sel:[0,1,0] op_sel_hi:[0,1,0]
	v_fma_mix_f32 v12, v8, v111, v12 op_sel_hi:[0,1,0]
	v_fma_mix_f32 v12, v9, v111, v12 op_sel:[0,1,0] op_sel_hi:[0,1,0]
	v_pk_mul_f32 v[48:49], v[6:7], v[106:107]
	v_pk_mul_f32 v[50:51], v[8:9], v[108:109]
	v_add_f32_dpp v12, v12, v12 row_ror:1 row_mask:0xf bank_mask:0xf bound_ctrl:1
	v_fma_mix_f32 v105, v6, v90, v180 op_sel_hi:[0,1,0]
	v_fma_mix_f32 v105, v7, v90, v105 op_sel:[0,1,0] op_sel_hi:[0,1,0]
	v_add_f32_dpp v12, v12, v12 row_ror:2 row_mask:0xf bank_mask:0xf bound_ctrl:1
	v_pk_fma_f32 v[48:49], v[118:119], v[72:73], v[48:49] op_sel:[0,1,0]
	v_pk_fma_f32 v[50:51], v[120:121], v[72:73], v[50:51] op_sel:[0,1,0]
	v_add_f32_dpp v12, v12, v12 row_ror:4 row_mask:0xf bank_mask:0xf bound_ctrl:1
	v_fma_mix_f32 v105, v8, v91, v105 op_sel_hi:[0,1,0]
	v_fma_mix_f32 v105, v9, v91, v105 op_sel:[0,1,0] op_sel_hi:[0,1,0]
	v_add_f32_dpp v12, v12, v12 row_ror:8 row_mask:0xf bank_mask:0xf bound_ctrl:1
	v_pk_fma_f32 v[6:7], v[114:115], v[12:13], v[48:49] op_sel_hi:[1,0,1] neg_lo:[1,0,0] neg_hi:[1,0,0]
	v_pk_fma_f32 v[8:9], v[116:117], v[12:13], v[50:51] op_sel_hi:[1,0,1] neg_lo:[1,0,0] neg_hi:[1,0,0]
	s_waitcnt lgkmcnt(0)
	v_fma_mix_f32 v12, v6, v20, v180 op_sel_hi:[0,1,0]
	v_fma_mix_f32 v12, v7, v20, v12 op_sel:[0,1,0] op_sel_hi:[0,1,0]
	v_fma_mix_f32 v12, v8, v21, v12 op_sel_hi:[0,1,0]
	v_fma_mix_f32 v12, v9, v21, v12 op_sel:[0,1,0] op_sel_hi:[0,1,0]
	v_pk_mul_f32 v[48:49], v[6:7], v[16:17]
	v_pk_mul_f32 v[50:51], v[8:9], v[18:19]
	v_add_f32_dpp v12, v12, v12 row_ror:1 row_mask:0xf bank_mask:0xf bound_ctrl:1
	v_fma_mix_f32 v61, v6, v112, v180 op_sel_hi:[0,1,0]
	v_fma_mix_f32 v61, v7, v112, v61 op_sel:[0,1,0] op_sel_hi:[0,1,0]
	v_add_f32_dpp v12, v12, v12 row_ror:2 row_mask:0xf bank_mask:0xf bound_ctrl:1
	v_pk_fma_f32 v[48:49], v[28:29], v[66:67], v[48:49] op_sel_hi:[1,0,1]
	v_pk_fma_f32 v[50:51], v[30:31], v[66:67], v[50:51] op_sel_hi:[1,0,1]
	v_add_f32_dpp v12, v12, v12 row_ror:4 row_mask:0xf bank_mask:0xf bound_ctrl:1
	v_fma_mix_f32 v61, v8, v113, v61 op_sel_hi:[0,1,0]
	v_fma_mix_f32 v61, v9, v113, v61 op_sel:[0,1,0] op_sel_hi:[0,1,0]
	v_add_f32_dpp v12, v12, v12 row_ror:8 row_mask:0xf bank_mask:0xf bound_ctrl:1
	v_pk_fma_f32 v[6:7], v[24:25], v[12:13], v[48:49] op_sel_hi:[1,0,1] neg_lo:[1,0,0] neg_hi:[1,0,0]
	v_pk_fma_f32 v[8:9], v[26:27], v[12:13], v[50:51] op_sel_hi:[1,0,1] neg_lo:[1,0,0] neg_hi:[1,0,0]
	ds_read_b128 v[88:91], v10 offset:35072
	ds_read_b128 v[84:87], v10 offset:34816
	ds_read_b128 v[96:99], v10 offset:35584
	ds_read_b128 v[92:95], v10 offset:35328
	ds_read_b128 v[110:113], v10 offset:36096
	ds_read_b128 v[106:109], v10 offset:35840
	ds_read_b128 v[118:121], v10 offset:36608
	ds_read_b128 v[114:117], v10 offset:36352
	ds_read_b128 v[70:73], v11 offset:2304
	v_add_f32_dpp v83, v83, v83 row_ror:8 row_mask:0xf bank_mask:0xc
	v_add_f32_dpp v83, v52, v52 row_ror:8 row_mask:0xf bank_mask:0x3
	v_add_f32_dpp v100, v100, v100 row_ror:8 row_mask:0xf bank_mask:0xc
	v_add_f32_dpp v100, v53, v53 row_ror:8 row_mask:0xf bank_mask:0x3
	v_add_f32_dpp v101, v101, v101 row_ror:8 row_mask:0xf bank_mask:0xc
	v_add_f32_dpp v101, v54, v54 row_ror:8 row_mask:0xf bank_mask:0x3
	v_add_f32_dpp v102, v102, v102 row_ror:8 row_mask:0xf bank_mask:0xc
	v_add_f32_dpp v102, v55, v55 row_ror:8 row_mask:0xf bank_mask:0x3
	v_add_f32_dpp v103, v103, v103 row_ror:8 row_mask:0xf bank_mask:0xc
	v_add_f32_dpp v103, v56, v56 row_ror:8 row_mask:0xf bank_mask:0x3
	v_add_f32_dpp v104, v104, v104 row_ror:8 row_mask:0xf bank_mask:0xc
	v_add_f32_dpp v104, v57, v57 row_ror:8 row_mask:0xf bank_mask:0x3
	v_add_f32_dpp v105, v105, v105 row_ror:8 row_mask:0xf bank_mask:0xc
	v_add_f32_dpp v105, v81, v81 row_ror:8 row_mask:0xf bank_mask:0x3
	v_add_f32_dpp v61, v61, v61 row_ror:8 row_mask:0xf bank_mask:0xc
	v_add_f32_dpp v61, v82, v82 row_ror:8 row_mask:0xf bank_mask:0x3
	v_add_f32_dpp v103, v103, v103 row_ror:4 row_mask:0xf bank_mask:0xa
	v_add_f32_dpp v103, v83, v83 row_ror:12 row_mask:0xf bank_mask:0x5
	v_add_f32_dpp v104, v104, v104 row_ror:4 row_mask:0xf bank_mask:0xa
	v_add_f32_dpp v104, v100, v100 row_ror:12 row_mask:0xf bank_mask:0x5
	v_add_f32_dpp v105, v105, v105 row_ror:4 row_mask:0xf bank_mask:0xa
	v_add_f32_dpp v105, v101, v101 row_ror:12 row_mask:0xf bank_mask:0x5
	v_add_f32_dpp v61, v61, v61 row_ror:4 row_mask:0xf bank_mask:0xa
	v_add_f32_dpp v61, v102, v102 row_ror:12 row_mask:0xf bank_mask:0x5
	v_cndmask_b32_e64 v62, v105, v103, s[38:39]
	v_cndmask_b32_e64 v63, v103, v105, s[38:39]
	v_cndmask_b32_e64 v64, v61, v104, s[38:39]
	v_cndmask_b32_e64 v65, v104, v61, s[38:39]
	v_add_f32_dpp v62, v63, v62 quad_perm:[2,3,0,1] row_mask:0xf bank_mask:0xf bound_ctrl:1
	s_nop 0
	v_add_f32_dpp v63, v65, v64 quad_perm:[2,3,0,1] row_mask:0xf bank_mask:0xf bound_ctrl:1
	v_cndmask_b32_e64 v65, v63, v62, s[40:41]
	v_cndmask_b32_e64 v62, v62, v63, s[40:41]
	s_nop 1
	v_add_f32_dpp v62, v62, v65 quad_perm:[1,0,3,2] row_mask:0xf bank_mask:0xf bound_ctrl:1
	v_cvt_pk_bf16_f32 v62, v62, v62
	global_store_short v[2:3], v62, off
	v_lshl_add_u64 v[2:3], v[2:3], 0, s[84:85]
	v_fma_mix_f32 v12, v6, v36, v180 op_sel_hi:[0,1,0]
	v_fma_mix_f32 v12, v7, v36, v12 op_sel:[0,1,0] op_sel_hi:[0,1,0]
	v_fma_mix_f32 v12, v8, v37, v12 op_sel_hi:[0,1,0]
	v_fma_mix_f32 v12, v9, v37, v12 op_sel:[0,1,0] op_sel_hi:[0,1,0]
	v_pk_mul_f32 v[48:49], v[6:7], v[32:33]
	v_pk_mul_f32 v[50:51], v[8:9], v[34:35]
	v_add_f32_dpp v12, v12, v12 row_ror:1 row_mask:0xf bank_mask:0xf bound_ctrl:1
	v_fma_mix_f32 v52, v6, v22, v180 op_sel_hi:[0,1,0]
	v_fma_mix_f32 v52, v7, v22, v52 op_sel:[0,1,0] op_sel_hi:[0,1,0]
	v_add_f32_dpp v12, v12, v12 row_ror:2 row_mask:0xf bank_mask:0xf bound_ctrl:1
	v_pk_fma_f32 v[48:49], v[44:45], v[66:67], v[48:49] op_sel:[0,1,0]
	v_pk_fma_f32 v[50:51], v[46:47], v[66:67], v[50:51] op_sel:[0,1,0]
	v_add_f32_dpp v12, v12, v12 row_ror:4 row_mask:0xf bank_mask:0xf bound_ctrl:1
	v_fma_mix_f32 v52, v8, v23, v52 op_sel_hi:[0,1,0]
	v_fma_mix_f32 v52, v9, v23, v52 op_sel:[0,1,0] op_sel_hi:[0,1,0]
	v_add_f32_dpp v12, v12, v12 row_ror:8 row_mask:0xf bank_mask:0xf bound_ctrl:1
	v_pk_fma_f32 v[6:7], v[40:41], v[12:13], v[48:49] op_sel_hi:[1,0,1] neg_lo:[1,0,0] neg_hi:[1,0,0]
	v_pk_fma_f32 v[8:9], v[42:43], v[12:13], v[50:51] op_sel_hi:[1,0,1] neg_lo:[1,0,0] neg_hi:[1,0,0]
	s_waitcnt lgkmcnt(1)
	v_fma_mix_f32 v12, v6, v88, v180 op_sel_hi:[0,1,0]
	v_fma_mix_f32 v12, v7, v88, v12 op_sel:[0,1,0] op_sel_hi:[0,1,0]
	v_fma_mix_f32 v12, v8, v89, v12 op_sel_hi:[0,1,0]
	v_fma_mix_f32 v12, v9, v89, v12 op_sel:[0,1,0] op_sel_hi:[0,1,0]
	v_pk_mul_f32 v[48:49], v[6:7], v[84:85]
	v_pk_mul_f32 v[50:51], v[8:9], v[86:87]
	v_add_f32_dpp v12, v12, v12 row_ror:1 row_mask:0xf bank_mask:0xf bound_ctrl:1
	v_fma_mix_f32 v53, v6, v38, v180 op_sel_hi:[0,1,0]
	v_fma_mix_f32 v53, v7, v38, v53 op_sel:[0,1,0] op_sel_hi:[0,1,0]
	v_add_f32_dpp v12, v12, v12 row_ror:2 row_mask:0xf bank_mask:0xf bound_ctrl:1
	v_pk_fma_f32 v[48:49], v[96:97], v[68:69], v[48:49] op_sel_hi:[1,0,1]
	v_pk_fma_f32 v[50:51], v[98:99], v[68:69], v[50:51] op_sel_hi:[1,0,1]
	v_add_f32_dpp v12, v12, v12 row_ror:4 row_mask:0xf bank_mask:0xf bound_ctrl:1
	v_fma_mix_f32 v53, v8, v39, v53 op_sel_hi:[0,1,0]
	v_fma_mix_f32 v53, v9, v39, v53 op_sel:[0,1,0] op_sel_hi:[0,1,0]
	v_add_f32_dpp v12, v12, v12 row_ror:8 row_mask:0xf bank_mask:0xf bound_ctrl:1
	v_pk_fma_f32 v[6:7], v[92:93], v[12:13], v[48:49] op_sel_hi:[1,0,1] neg_lo:[1,0,0] neg_hi:[1,0,0]
	v_pk_fma_f32 v[8:9], v[94:95], v[12:13], v[50:51] op_sel_hi:[1,0,1] neg_lo:[1,0,0] neg_hi:[1,0,0]
	ds_read_b128 v[20:23], v10 offset:37120
	ds_read_b128 v[16:19], v10 offset:36864
	ds_read_b128 v[28:31], v10 offset:37632
	ds_read_b128 v[24:27], v10 offset:37376
	ds_read_b128 v[36:39], v10 offset:38144
	ds_read_b128 v[32:35], v10 offset:37888
	ds_read_b128 v[44:47], v10 offset:38656
	ds_read_b128 v[40:43], v10 offset:38400
	v_fma_mix_f32 v12, v6, v110, v180 op_sel_hi:[0,1,0]
	v_fma_mix_f32 v12, v7, v110, v12 op_sel:[0,1,0] op_sel_hi:[0,1,0]
	v_fma_mix_f32 v12, v8, v111, v12 op_sel_hi:[0,1,0]
	v_fma_mix_f32 v12, v9, v111, v12 op_sel:[0,1,0] op_sel_hi:[0,1,0]
	v_pk_mul_f32 v[48:49], v[6:7], v[106:107]
	v_pk_mul_f32 v[50:51], v[8:9], v[108:109]
	v_add_f32_dpp v12, v12, v12 row_ror:1 row_mask:0xf bank_mask:0xf bound_ctrl:1
	v_fma_mix_f32 v54, v6, v90, v180 op_sel_hi:[0,1,0]
	v_fma_mix_f32 v54, v7, v90, v54 op_sel:[0,1,0] op_sel_hi:[0,1,0]
	v_add_f32_dpp v12, v12, v12 row_ror:2 row_mask:0xf bank_mask:0xf bound_ctrl:1
	v_pk_fma_f32 v[48:49], v[118:119], v[68:69], v[48:49] op_sel:[0,1,0]
	v_pk_fma_f32 v[50:51], v[120:121], v[68:69], v[50:51] op_sel:[0,1,0]
	v_add_f32_dpp v12, v12, v12 row_ror:4 row_mask:0xf bank_mask:0xf bound_ctrl:1
	v_fma_mix_f32 v54, v8, v91, v54 op_sel_hi:[0,1,0]
	v_fma_mix_f32 v54, v9, v91, v54 op_sel:[0,1,0] op_sel_hi:[0,1,0]
	v_add_f32_dpp v12, v12, v12 row_ror:8 row_mask:0xf bank_mask:0xf bound_ctrl:1
	v_pk_fma_f32 v[6:7], v[114:115], v[12:13], v[48:49] op_sel_hi:[1,0,1] neg_lo:[1,0,0] neg_hi:[1,0,0]
	v_pk_fma_f32 v[8:9], v[116:117], v[12:13], v[50:51] op_sel_hi:[1,0,1] neg_lo:[1,0,0] neg_hi:[1,0,0]
	s_waitcnt lgkmcnt(0)
	v_fma_mix_f32 v12, v6, v20, v180 op_sel_hi:[0,1,0]
	v_fma_mix_f32 v12, v7, v20, v12 op_sel:[0,1,0] op_sel_hi:[0,1,0]
	v_fma_mix_f32 v12, v8, v21, v12 op_sel_hi:[0,1,0]
	v_fma_mix_f32 v12, v9, v21, v12 op_sel:[0,1,0] op_sel_hi:[0,1,0]
	v_pk_mul_f32 v[48:49], v[6:7], v[16:17]
	v_pk_mul_f32 v[50:51], v[8:9], v[18:19]
	v_add_f32_dpp v12, v12, v12 row_ror:1 row_mask:0xf bank_mask:0xf bound_ctrl:1
	v_fma_mix_f32 v55, v6, v112, v180 op_sel_hi:[0,1,0]
	v_fma_mix_f32 v55, v7, v112, v55 op_sel:[0,1,0] op_sel_hi:[0,1,0]
	v_add_f32_dpp v12, v12, v12 row_ror:2 row_mask:0xf bank_mask:0xf bound_ctrl:1
	v_pk_fma_f32 v[48:49], v[28:29], v[70:71], v[48:49] op_sel_hi:[1,0,1]
	v_pk_fma_f32 v[50:51], v[30:31], v[70:71], v[50:51] op_sel_hi:[1,0,1]
	v_add_f32_dpp v12, v12, v12 row_ror:4 row_mask:0xf bank_mask:0xf bound_ctrl:1
	v_fma_mix_f32 v55, v8, v113, v55 op_sel_hi:[0,1,0]
	v_fma_mix_f32 v55, v9, v113, v55 op_sel:[0,1,0] op_sel_hi:[0,1,0]
	v_add_f32_dpp v12, v12, v12 row_ror:8 row_mask:0xf bank_mask:0xf bound_ctrl:1
	v_pk_fma_f32 v[6:7], v[24:25], v[12:13], v[48:49] op_sel_hi:[1,0,1] neg_lo:[1,0,0] neg_hi:[1,0,0]
	v_pk_fma_f32 v[8:9], v[26:27], v[12:13], v[50:51] op_sel_hi:[1,0,1] neg_lo:[1,0,0] neg_hi:[1,0,0]
	ds_read_b128 v[88:91], v10 offset:39168
	ds_read_b128 v[84:87], v10 offset:38912
	ds_read_b128 v[96:99], v10 offset:39680
	ds_read_b128 v[92:95], v10 offset:39424
	ds_read_b128 v[110:113], v10 offset:40192
	ds_read_b128 v[106:109], v10 offset:39936
	ds_read_b128 v[118:121], v10 offset:40704
	ds_read_b128 v[114:117], v10 offset:40448
	ds_read_b128 v[66:69], v11 offset:2560
	v_fma_mix_f32 v12, v6, v36, v180 op_sel_hi:[0,1,0]
	v_fma_mix_f32 v12, v7, v36, v12 op_sel:[0,1,0] op_sel_hi:[0,1,0]
	v_fma_mix_f32 v12, v8, v37, v12 op_sel_hi:[0,1,0]
	v_fma_mix_f32 v12, v9, v37, v12 op_sel:[0,1,0] op_sel_hi:[0,1,0]
	v_pk_mul_f32 v[48:49], v[6:7], v[32:33]
	v_pk_mul_f32 v[50:51], v[8:9], v[34:35]
	v_add_f32_dpp v12, v12, v12 row_ror:1 row_mask:0xf bank_mask:0xf bound_ctrl:1
	v_fma_mix_f32 v56, v6, v22, v180 op_sel_hi:[0,1,0]
	v_fma_mix_f32 v56, v7, v22, v56 op_sel:[0,1,0] op_sel_hi:[0,1,0]
	v_add_f32_dpp v12, v12, v12 row_ror:2 row_mask:0xf bank_mask:0xf bound_ctrl:1
	v_pk_fma_f32 v[48:49], v[44:45], v[70:71], v[48:49] op_sel:[0,1,0]
	v_pk_fma_f32 v[50:51], v[46:47], v[70:71], v[50:51] op_sel:[0,1,0]
	v_add_f32_dpp v12, v12, v12 row_ror:4 row_mask:0xf bank_mask:0xf bound_ctrl:1
	v_fma_mix_f32 v56, v8, v23, v56 op_sel_hi:[0,1,0]
	v_fma_mix_f32 v56, v9, v23, v56 op_sel:[0,1,0] op_sel_hi:[0,1,0]
	v_add_f32_dpp v12, v12, v12 row_ror:8 row_mask:0xf bank_mask:0xf bound_ctrl:1
	v_pk_fma_f32 v[6:7], v[40:41], v[12:13], v[48:49] op_sel_hi:[1,0,1] neg_lo:[1,0,0] neg_hi:[1,0,0]
	v_pk_fma_f32 v[8:9], v[42:43], v[12:13], v[50:51] op_sel_hi:[1,0,1] neg_lo:[1,0,0] neg_hi:[1,0,0]
	s_waitcnt lgkmcnt(1)
	v_fma_mix_f32 v12, v6, v88, v180 op_sel_hi:[0,1,0]
	v_fma_mix_f32 v12, v7, v88, v12 op_sel:[0,1,0] op_sel_hi:[0,1,0]
	v_fma_mix_f32 v12, v8, v89, v12 op_sel_hi:[0,1,0]
	v_fma_mix_f32 v12, v9, v89, v12 op_sel:[0,1,0] op_sel_hi:[0,1,0]
	v_pk_mul_f32 v[48:49], v[6:7], v[84:85]
	v_pk_mul_f32 v[50:51], v[8:9], v[86:87]
	v_add_f32_dpp v12, v12, v12 row_ror:1 row_mask:0xf bank_mask:0xf bound_ctrl:1
	v_fma_mix_f32 v57, v6, v38, v180 op_sel_hi:[0,1,0]
	v_fma_mix_f32 v57, v7, v38, v57 op_sel:[0,1,0] op_sel_hi:[0,1,0]
	v_add_f32_dpp v12, v12, v12 row_ror:2 row_mask:0xf bank_mask:0xf bound_ctrl:1
	v_pk_fma_f32 v[48:49], v[96:97], v[72:73], v[48:49] op_sel_hi:[1,0,1]
	v_pk_fma_f32 v[50:51], v[98:99], v[72:73], v[50:51] op_sel_hi:[1,0,1]
	v_add_f32_dpp v12, v12, v12 row_ror:4 row_mask:0xf bank_mask:0xf bound_ctrl:1
	v_fma_mix_f32 v57, v8, v39, v57 op_sel_hi:[0,1,0]
	v_fma_mix_f32 v57, v9, v39, v57 op_sel:[0,1,0] op_sel_hi:[0,1,0]
	v_add_f32_dpp v12, v12, v12 row_ror:8 row_mask:0xf bank_mask:0xf bound_ctrl:1
	v_pk_fma_f32 v[6:7], v[92:93], v[12:13], v[48:49] op_sel_hi:[1,0,1] neg_lo:[1,0,0] neg_hi:[1,0,0]
	v_pk_fma_f32 v[8:9], v[94:95], v[12:13], v[50:51] op_sel_hi:[1,0,1] neg_lo:[1,0,0] neg_hi:[1,0,0]
	ds_read_b128 v[20:23], v10 offset:41216
	ds_read_b128 v[16:19], v10 offset:40960
	ds_read_b128 v[28:31], v10 offset:41728
	ds_read_b128 v[24:27], v10 offset:41472
	ds_read_b128 v[36:39], v10 offset:42240
	ds_read_b128 v[32:35], v10 offset:41984
	ds_read_b128 v[44:47], v10 offset:42752
	ds_read_b128 v[40:43], v10 offset:42496
	v_fma_mix_f32 v12, v6, v110, v180 op_sel_hi:[0,1,0]
	v_fma_mix_f32 v12, v7, v110, v12 op_sel:[0,1,0] op_sel_hi:[0,1,0]
	v_fma_mix_f32 v12, v8, v111, v12 op_sel_hi:[0,1,0]
	v_fma_mix_f32 v12, v9, v111, v12 op_sel:[0,1,0] op_sel_hi:[0,1,0]
	v_pk_mul_f32 v[48:49], v[6:7], v[106:107]
	v_pk_mul_f32 v[50:51], v[8:9], v[108:109]
	v_add_f32_dpp v12, v12, v12 row_ror:1 row_mask:0xf bank_mask:0xf bound_ctrl:1
	v_fma_mix_f32 v81, v6, v90, v180 op_sel_hi:[0,1,0]
	v_fma_mix_f32 v81, v7, v90, v81 op_sel:[0,1,0] op_sel_hi:[0,1,0]
	v_add_f32_dpp v12, v12, v12 row_ror:2 row_mask:0xf bank_mask:0xf bound_ctrl:1
	v_pk_fma_f32 v[48:49], v[118:119], v[72:73], v[48:49] op_sel:[0,1,0]
	v_pk_fma_f32 v[50:51], v[120:121], v[72:73], v[50:51] op_sel:[0,1,0]
	v_add_f32_dpp v12, v12, v12 row_ror:4 row_mask:0xf bank_mask:0xf bound_ctrl:1
	v_fma_mix_f32 v81, v8, v91, v81 op_sel_hi:[0,1,0]
	v_fma_mix_f32 v81, v9, v91, v81 op_sel:[0,1,0] op_sel_hi:[0,1,0]
	v_add_f32_dpp v12, v12, v12 row_ror:8 row_mask:0xf bank_mask:0xf bound_ctrl:1
	v_pk_fma_f32 v[6:7], v[114:115], v[12:13], v[48:49] op_sel_hi:[1,0,1] neg_lo:[1,0,0] neg_hi:[1,0,0]
	v_pk_fma_f32 v[8:9], v[116:117], v[12:13], v[50:51] op_sel_hi:[1,0,1] neg_lo:[1,0,0] neg_hi:[1,0,0]
	s_waitcnt lgkmcnt(0)
	v_fma_mix_f32 v12, v6, v20, v180 op_sel_hi:[0,1,0]
	v_fma_mix_f32 v12, v7, v20, v12 op_sel:[0,1,0] op_sel_hi:[0,1,0]
	v_fma_mix_f32 v12, v8, v21, v12 op_sel_hi:[0,1,0]
	v_fma_mix_f32 v12, v9, v21, v12 op_sel:[0,1,0] op_sel_hi:[0,1,0]
	v_pk_mul_f32 v[48:49], v[6:7], v[16:17]
	v_pk_mul_f32 v[50:51], v[8:9], v[18:19]
	v_add_f32_dpp v12, v12, v12 row_ror:1 row_mask:0xf bank_mask:0xf bound_ctrl:1
	v_fma_mix_f32 v82, v6, v112, v180 op_sel_hi:[0,1,0]
	v_fma_mix_f32 v82, v7, v112, v82 op_sel:[0,1,0] op_sel_hi:[0,1,0]
	v_add_f32_dpp v12, v12, v12 row_ror:2 row_mask:0xf bank_mask:0xf bound_ctrl:1
	v_pk_fma_f32 v[48:49], v[28:29], v[66:67], v[48:49] op_sel_hi:[1,0,1]
	v_pk_fma_f32 v[50:51], v[30:31], v[66:67], v[50:51] op_sel_hi:[1,0,1]
	v_add_f32_dpp v12, v12, v12 row_ror:4 row_mask:0xf bank_mask:0xf bound_ctrl:1
	v_fma_mix_f32 v82, v8, v113, v82 op_sel_hi:[0,1,0]
	v_fma_mix_f32 v82, v9, v113, v82 op_sel:[0,1,0] op_sel_hi:[0,1,0]
	v_add_f32_dpp v12, v12, v12 row_ror:8 row_mask:0xf bank_mask:0xf bound_ctrl:1
	v_pk_fma_f32 v[6:7], v[24:25], v[12:13], v[48:49] op_sel_hi:[1,0,1] neg_lo:[1,0,0] neg_hi:[1,0,0]
	v_pk_fma_f32 v[8:9], v[26:27], v[12:13], v[50:51] op_sel_hi:[1,0,1] neg_lo:[1,0,0] neg_hi:[1,0,0]
	ds_read_b128 v[88:91], v10 offset:43264
	ds_read_b128 v[84:87], v10 offset:43008
	ds_read_b128 v[96:99], v10 offset:43776
	ds_read_b128 v[92:95], v10 offset:43520
	ds_read_b128 v[110:113], v10 offset:44288
	ds_read_b128 v[106:109], v10 offset:44032
	ds_read_b128 v[118:121], v10 offset:44800
	ds_read_b128 v[114:117], v10 offset:44544
	ds_read_b128 v[70:73], v11 offset:2816
	v_fma_mix_f32 v12, v6, v36, v180 op_sel_hi:[0,1,0]
	v_fma_mix_f32 v12, v7, v36, v12 op_sel:[0,1,0] op_sel_hi:[0,1,0]
	v_fma_mix_f32 v12, v8, v37, v12 op_sel_hi:[0,1,0]
	v_fma_mix_f32 v12, v9, v37, v12 op_sel:[0,1,0] op_sel_hi:[0,1,0]
	v_pk_mul_f32 v[48:49], v[6:7], v[32:33]
	v_pk_mul_f32 v[50:51], v[8:9], v[34:35]
	v_add_f32_dpp v12, v12, v12 row_ror:1 row_mask:0xf bank_mask:0xf bound_ctrl:1
	v_fma_mix_f32 v83, v6, v22, v180 op_sel_hi:[0,1,0]
	v_fma_mix_f32 v83, v7, v22, v83 op_sel:[0,1,0] op_sel_hi:[0,1,0]
	v_add_f32_dpp v12, v12, v12 row_ror:2 row_mask:0xf bank_mask:0xf bound_ctrl:1
	v_pk_fma_f32 v[48:49], v[44:45], v[66:67], v[48:49] op_sel:[0,1,0]
	v_pk_fma_f32 v[50:51], v[46:47], v[66:67], v[50:51] op_sel:[0,1,0]
	v_add_f32_dpp v12, v12, v12 row_ror:4 row_mask:0xf bank_mask:0xf bound_ctrl:1
	v_fma_mix_f32 v83, v8, v23, v83 op_sel_hi:[0,1,0]
	v_fma_mix_f32 v83, v9, v23, v83 op_sel:[0,1,0] op_sel_hi:[0,1,0]
	v_add_f32_dpp v12, v12, v12 row_ror:8 row_mask:0xf bank_mask:0xf bound_ctrl:1
	v_pk_fma_f32 v[6:7], v[40:41], v[12:13], v[48:49] op_sel_hi:[1,0,1] neg_lo:[1,0,0] neg_hi:[1,0,0]
	v_pk_fma_f32 v[8:9], v[42:43], v[12:13], v[50:51] op_sel_hi:[1,0,1] neg_lo:[1,0,0] neg_hi:[1,0,0]
	s_waitcnt lgkmcnt(1)
	v_fma_mix_f32 v12, v6, v88, v180 op_sel_hi:[0,1,0]
	v_fma_mix_f32 v12, v7, v88, v12 op_sel:[0,1,0] op_sel_hi:[0,1,0]
	v_fma_mix_f32 v12, v8, v89, v12 op_sel_hi:[0,1,0]
	v_fma_mix_f32 v12, v9, v89, v12 op_sel:[0,1,0] op_sel_hi:[0,1,0]
	v_pk_mul_f32 v[48:49], v[6:7], v[84:85]
	v_pk_mul_f32 v[50:51], v[8:9], v[86:87]
	v_add_f32_dpp v12, v12, v12 row_ror:1 row_mask:0xf bank_mask:0xf bound_ctrl:1
	v_fma_mix_f32 v100, v6, v38, v180 op_sel_hi:[0,1,0]
	v_fma_mix_f32 v100, v7, v38, v100 op_sel:[0,1,0] op_sel_hi:[0,1,0]
	v_add_f32_dpp v12, v12, v12 row_ror:2 row_mask:0xf bank_mask:0xf bound_ctrl:1
	v_pk_fma_f32 v[48:49], v[96:97], v[68:69], v[48:49] op_sel_hi:[1,0,1]
	v_pk_fma_f32 v[50:51], v[98:99], v[68:69], v[50:51] op_sel_hi:[1,0,1]
	v_add_f32_dpp v12, v12, v12 row_ror:4 row_mask:0xf bank_mask:0xf bound_ctrl:1
	v_fma_mix_f32 v100, v8, v39, v100 op_sel_hi:[0,1,0]
	v_fma_mix_f32 v100, v9, v39, v100 op_sel:[0,1,0] op_sel_hi:[0,1,0]
	v_add_f32_dpp v12, v12, v12 row_ror:8 row_mask:0xf bank_mask:0xf bound_ctrl:1
	v_pk_fma_f32 v[6:7], v[92:93], v[12:13], v[48:49] op_sel_hi:[1,0,1] neg_lo:[1,0,0] neg_hi:[1,0,0]
	v_pk_fma_f32 v[8:9], v[94:95], v[12:13], v[50:51] op_sel_hi:[1,0,1] neg_lo:[1,0,0] neg_hi:[1,0,0]
	ds_read_b128 v[20:23], v10 offset:45312
	ds_read_b128 v[16:19], v10 offset:45056
	ds_read_b128 v[28:31], v10 offset:45824
	ds_read_b128 v[24:27], v10 offset:45568
	ds_read_b128 v[36:39], v10 offset:46336
	ds_read_b128 v[32:35], v10 offset:46080
	ds_read_b128 v[44:47], v10 offset:46848
	ds_read_b128 v[40:43], v10 offset:46592
	v_fma_mix_f32 v12, v6, v110, v180 op_sel_hi:[0,1,0]
	v_fma_mix_f32 v12, v7, v110, v12 op_sel:[0,1,0] op_sel_hi:[0,1,0]
	v_fma_mix_f32 v12, v8, v111, v12 op_sel_hi:[0,1,0]
	v_fma_mix_f32 v12, v9, v111, v12 op_sel:[0,1,0] op_sel_hi:[0,1,0]
	v_pk_mul_f32 v[48:49], v[6:7], v[106:107]
	v_pk_mul_f32 v[50:51], v[8:9], v[108:109]
	v_add_f32_dpp v12, v12, v12 row_ror:1 row_mask:0xf bank_mask:0xf bound_ctrl:1
	v_fma_mix_f32 v101, v6, v90, v180 op_sel_hi:[0,1,0]
	v_fma_mix_f32 v101, v7, v90, v101 op_sel:[0,1,0] op_sel_hi:[0,1,0]
	v_add_f32_dpp v12, v12, v12 row_ror:2 row_mask:0xf bank_mask:0xf bound_ctrl:1
	v_pk_fma_f32 v[48:49], v[118:119], v[68:69], v[48:49] op_sel:[0,1,0]
	v_pk_fma_f32 v[50:51], v[120:121], v[68:69], v[50:51] op_sel:[0,1,0]
	v_add_f32_dpp v12, v12, v12 row_ror:4 row_mask:0xf bank_mask:0xf bound_ctrl:1
	v_fma_mix_f32 v101, v8, v91, v101 op_sel_hi:[0,1,0]
	v_fma_mix_f32 v101, v9, v91, v101 op_sel:[0,1,0] op_sel_hi:[0,1,0]
	v_add_f32_dpp v12, v12, v12 row_ror:8 row_mask:0xf bank_mask:0xf bound_ctrl:1
	v_pk_fma_f32 v[6:7], v[114:115], v[12:13], v[48:49] op_sel_hi:[1,0,1] neg_lo:[1,0,0] neg_hi:[1,0,0]
	v_pk_fma_f32 v[8:9], v[116:117], v[12:13], v[50:51] op_sel_hi:[1,0,1] neg_lo:[1,0,0] neg_hi:[1,0,0]
	s_waitcnt lgkmcnt(0)
	v_fma_mix_f32 v12, v6, v20, v180 op_sel_hi:[0,1,0]
	v_fma_mix_f32 v12, v7, v20, v12 op_sel:[0,1,0] op_sel_hi:[0,1,0]
	v_fma_mix_f32 v12, v8, v21, v12 op_sel_hi:[0,1,0]
	v_fma_mix_f32 v12, v9, v21, v12 op_sel:[0,1,0] op_sel_hi:[0,1,0]
	v_pk_mul_f32 v[48:49], v[6:7], v[16:17]
	v_pk_mul_f32 v[50:51], v[8:9], v[18:19]
	v_add_f32_dpp v12, v12, v12 row_ror:1 row_mask:0xf bank_mask:0xf bound_ctrl:1
	v_fma_mix_f32 v102, v6, v112, v180 op_sel_hi:[0,1,0]
	v_fma_mix_f32 v102, v7, v112, v102 op_sel:[0,1,0] op_sel_hi:[0,1,0]
	v_add_f32_dpp v12, v12, v12 row_ror:2 row_mask:0xf bank_mask:0xf bound_ctrl:1
	v_pk_fma_f32 v[48:49], v[28:29], v[70:71], v[48:49] op_sel_hi:[1,0,1]
	v_pk_fma_f32 v[50:51], v[30:31], v[70:71], v[50:51] op_sel_hi:[1,0,1]
	v_add_f32_dpp v12, v12, v12 row_ror:4 row_mask:0xf bank_mask:0xf bound_ctrl:1
	v_fma_mix_f32 v102, v8, v113, v102 op_sel_hi:[0,1,0]
	v_fma_mix_f32 v102, v9, v113, v102 op_sel:[0,1,0] op_sel_hi:[0,1,0]
	v_add_f32_dpp v12, v12, v12 row_ror:8 row_mask:0xf bank_mask:0xf bound_ctrl:1
	v_pk_fma_f32 v[6:7], v[24:25], v[12:13], v[48:49] op_sel_hi:[1,0,1] neg_lo:[1,0,0] neg_hi:[1,0,0]
	v_pk_fma_f32 v[8:9], v[26:27], v[12:13], v[50:51] op_sel_hi:[1,0,1] neg_lo:[1,0,0] neg_hi:[1,0,0]
	ds_read_b128 v[88:91], v10 offset:47360
	ds_read_b128 v[84:87], v10 offset:47104
	ds_read_b128 v[96:99], v10 offset:47872
	ds_read_b128 v[92:95], v10 offset:47616
	ds_read_b128 v[110:113], v10 offset:48384
	ds_read_b128 v[106:109], v10 offset:48128
	ds_read_b128 v[118:121], v10 offset:48896
	ds_read_b128 v[114:117], v10 offset:48640
	ds_read_b128 v[66:69], v11 offset:3072
	v_fma_mix_f32 v12, v6, v36, v180 op_sel_hi:[0,1,0]
	v_fma_mix_f32 v12, v7, v36, v12 op_sel:[0,1,0] op_sel_hi:[0,1,0]
	v_fma_mix_f32 v12, v8, v37, v12 op_sel_hi:[0,1,0]
	v_fma_mix_f32 v12, v9, v37, v12 op_sel:[0,1,0] op_sel_hi:[0,1,0]
	v_pk_mul_f32 v[48:49], v[6:7], v[32:33]
	v_pk_mul_f32 v[50:51], v[8:9], v[34:35]
	v_add_f32_dpp v12, v12, v12 row_ror:1 row_mask:0xf bank_mask:0xf bound_ctrl:1
	v_fma_mix_f32 v103, v6, v22, v180 op_sel_hi:[0,1,0]
	v_fma_mix_f32 v103, v7, v22, v103 op_sel:[0,1,0] op_sel_hi:[0,1,0]
	v_add_f32_dpp v12, v12, v12 row_ror:2 row_mask:0xf bank_mask:0xf bound_ctrl:1
	v_pk_fma_f32 v[48:49], v[44:45], v[70:71], v[48:49] op_sel:[0,1,0]
	v_pk_fma_f32 v[50:51], v[46:47], v[70:71], v[50:51] op_sel:[0,1,0]
	v_add_f32_dpp v12, v12, v12 row_ror:4 row_mask:0xf bank_mask:0xf bound_ctrl:1
	v_fma_mix_f32 v103, v8, v23, v103 op_sel_hi:[0,1,0]
	v_fma_mix_f32 v103, v9, v23, v103 op_sel:[0,1,0] op_sel_hi:[0,1,0]
	v_add_f32_dpp v12, v12, v12 row_ror:8 row_mask:0xf bank_mask:0xf bound_ctrl:1
	v_pk_fma_f32 v[6:7], v[40:41], v[12:13], v[48:49] op_sel_hi:[1,0,1] neg_lo:[1,0,0] neg_hi:[1,0,0]
	v_pk_fma_f32 v[8:9], v[42:43], v[12:13], v[50:51] op_sel_hi:[1,0,1] neg_lo:[1,0,0] neg_hi:[1,0,0]
	s_waitcnt lgkmcnt(1)
	v_fma_mix_f32 v12, v6, v88, v180 op_sel_hi:[0,1,0]
	v_fma_mix_f32 v12, v7, v88, v12 op_sel:[0,1,0] op_sel_hi:[0,1,0]
	v_fma_mix_f32 v12, v8, v89, v12 op_sel_hi:[0,1,0]
	v_fma_mix_f32 v12, v9, v89, v12 op_sel:[0,1,0] op_sel_hi:[0,1,0]
	v_pk_mul_f32 v[48:49], v[6:7], v[84:85]
	v_pk_mul_f32 v[50:51], v[8:9], v[86:87]
	v_add_f32_dpp v12, v12, v12 row_ror:1 row_mask:0xf bank_mask:0xf bound_ctrl:1
	v_fma_mix_f32 v104, v6, v38, v180 op_sel_hi:[0,1,0]
	v_fma_mix_f32 v104, v7, v38, v104 op_sel:[0,1,0] op_sel_hi:[0,1,0]
	v_add_f32_dpp v12, v12, v12 row_ror:2 row_mask:0xf bank_mask:0xf bound_ctrl:1
	v_pk_fma_f32 v[48:49], v[96:97], v[72:73], v[48:49] op_sel_hi:[1,0,1]
	v_pk_fma_f32 v[50:51], v[98:99], v[72:73], v[50:51] op_sel_hi:[1,0,1]
	v_add_f32_dpp v12, v12, v12 row_ror:4 row_mask:0xf bank_mask:0xf bound_ctrl:1
	v_fma_mix_f32 v104, v8, v39, v104 op_sel_hi:[0,1,0]
	v_fma_mix_f32 v104, v9, v39, v104 op_sel:[0,1,0] op_sel_hi:[0,1,0]
	v_add_f32_dpp v12, v12, v12 row_ror:8 row_mask:0xf bank_mask:0xf bound_ctrl:1
	v_pk_fma_f32 v[6:7], v[92:93], v[12:13], v[48:49] op_sel_hi:[1,0,1] neg_lo:[1,0,0] neg_hi:[1,0,0]
	v_pk_fma_f32 v[8:9], v[94:95], v[12:13], v[50:51] op_sel_hi:[1,0,1] neg_lo:[1,0,0] neg_hi:[1,0,0]
	ds_read_b128 v[20:23], v10 offset:49408
	ds_read_b128 v[16:19], v10 offset:49152
	ds_read_b128 v[28:31], v10 offset:49920
	ds_read_b128 v[24:27], v10 offset:49664
	ds_read_b128 v[36:39], v10 offset:50432
	ds_read_b128 v[32:35], v10 offset:50176
	ds_read_b128 v[44:47], v10 offset:50944
	ds_read_b128 v[40:43], v10 offset:50688
	v_fma_mix_f32 v12, v6, v110, v180 op_sel_hi:[0,1,0]
	v_fma_mix_f32 v12, v7, v110, v12 op_sel:[0,1,0] op_sel_hi:[0,1,0]
	v_fma_mix_f32 v12, v8, v111, v12 op_sel_hi:[0,1,0]
	v_fma_mix_f32 v12, v9, v111, v12 op_sel:[0,1,0] op_sel_hi:[0,1,0]
	v_pk_mul_f32 v[48:49], v[6:7], v[106:107]
	v_pk_mul_f32 v[50:51], v[8:9], v[108:109]
	v_add_f32_dpp v12, v12, v12 row_ror:1 row_mask:0xf bank_mask:0xf bound_ctrl:1
	v_fma_mix_f32 v105, v6, v90, v180 op_sel_hi:[0,1,0]
	v_fma_mix_f32 v105, v7, v90, v105 op_sel:[0,1,0] op_sel_hi:[0,1,0]
	v_add_f32_dpp v12, v12, v12 row_ror:2 row_mask:0xf bank_mask:0xf bound_ctrl:1
	v_pk_fma_f32 v[48:49], v[118:119], v[72:73], v[48:49] op_sel:[0,1,0]
	v_pk_fma_f32 v[50:51], v[120:121], v[72:73], v[50:51] op_sel:[0,1,0]
	v_add_f32_dpp v12, v12, v12 row_ror:4 row_mask:0xf bank_mask:0xf bound_ctrl:1
	v_fma_mix_f32 v105, v8, v91, v105 op_sel_hi:[0,1,0]
	v_fma_mix_f32 v105, v9, v91, v105 op_sel:[0,1,0] op_sel_hi:[0,1,0]
	v_add_f32_dpp v12, v12, v12 row_ror:8 row_mask:0xf bank_mask:0xf bound_ctrl:1
	v_pk_fma_f32 v[6:7], v[114:115], v[12:13], v[48:49] op_sel_hi:[1,0,1] neg_lo:[1,0,0] neg_hi:[1,0,0]
	v_pk_fma_f32 v[8:9], v[116:117], v[12:13], v[50:51] op_sel_hi:[1,0,1] neg_lo:[1,0,0] neg_hi:[1,0,0]
	s_waitcnt lgkmcnt(0)
	v_fma_mix_f32 v12, v6, v20, v180 op_sel_hi:[0,1,0]
	v_fma_mix_f32 v12, v7, v20, v12 op_sel:[0,1,0] op_sel_hi:[0,1,0]
	v_fma_mix_f32 v12, v8, v21, v12 op_sel_hi:[0,1,0]
	v_fma_mix_f32 v12, v9, v21, v12 op_sel:[0,1,0] op_sel_hi:[0,1,0]
	v_pk_mul_f32 v[48:49], v[6:7], v[16:17]
	v_pk_mul_f32 v[50:51], v[8:9], v[18:19]
	v_add_f32_dpp v12, v12, v12 row_ror:1 row_mask:0xf bank_mask:0xf bound_ctrl:1
	v_fma_mix_f32 v61, v6, v112, v180 op_sel_hi:[0,1,0]
	v_fma_mix_f32 v61, v7, v112, v61 op_sel:[0,1,0] op_sel_hi:[0,1,0]
	v_add_f32_dpp v12, v12, v12 row_ror:2 row_mask:0xf bank_mask:0xf bound_ctrl:1
	v_pk_fma_f32 v[48:49], v[28:29], v[66:67], v[48:49] op_sel_hi:[1,0,1]
	v_pk_fma_f32 v[50:51], v[30:31], v[66:67], v[50:51] op_sel_hi:[1,0,1]
	v_add_f32_dpp v12, v12, v12 row_ror:4 row_mask:0xf bank_mask:0xf bound_ctrl:1
	v_fma_mix_f32 v61, v8, v113, v61 op_sel_hi:[0,1,0]
	v_fma_mix_f32 v61, v9, v113, v61 op_sel:[0,1,0] op_sel_hi:[0,1,0]
	v_add_f32_dpp v12, v12, v12 row_ror:8 row_mask:0xf bank_mask:0xf bound_ctrl:1
	v_pk_fma_f32 v[6:7], v[24:25], v[12:13], v[48:49] op_sel_hi:[1,0,1] neg_lo:[1,0,0] neg_hi:[1,0,0]
	v_pk_fma_f32 v[8:9], v[26:27], v[12:13], v[50:51] op_sel_hi:[1,0,1] neg_lo:[1,0,0] neg_hi:[1,0,0]
	ds_read_b128 v[88:91], v10 offset:51456
	ds_read_b128 v[84:87], v10 offset:51200
	ds_read_b128 v[96:99], v10 offset:51968
	ds_read_b128 v[92:95], v10 offset:51712
	ds_read_b128 v[110:113], v10 offset:52480
	ds_read_b128 v[106:109], v10 offset:52224
	ds_read_b128 v[118:121], v10 offset:52992
	ds_read_b128 v[114:117], v10 offset:52736
	ds_read_b128 v[70:73], v11 offset:3328
	v_add_f32_dpp v83, v83, v83 row_ror:8 row_mask:0xf bank_mask:0xc
	v_add_f32_dpp v83, v52, v52 row_ror:8 row_mask:0xf bank_mask:0x3
	v_add_f32_dpp v100, v100, v100 row_ror:8 row_mask:0xf bank_mask:0xc
	v_add_f32_dpp v100, v53, v53 row_ror:8 row_mask:0xf bank_mask:0x3
	v_add_f32_dpp v101, v101, v101 row_ror:8 row_mask:0xf bank_mask:0xc
	v_add_f32_dpp v101, v54, v54 row_ror:8 row_mask:0xf bank_mask:0x3
	v_add_f32_dpp v102, v102, v102 row_ror:8 row_mask:0xf bank_mask:0xc
	v_add_f32_dpp v102, v55, v55 row_ror:8 row_mask:0xf bank_mask:0x3
	v_add_f32_dpp v103, v103, v103 row_ror:8 row_mask:0xf bank_mask:0xc
	v_add_f32_dpp v103, v56, v56 row_ror:8 row_mask:0xf bank_mask:0x3
	v_add_f32_dpp v104, v104, v104 row_ror:8 row_mask:0xf bank_mask:0xc
	v_add_f32_dpp v104, v57, v57 row_ror:8 row_mask:0xf bank_mask:0x3
	v_add_f32_dpp v105, v105, v105 row_ror:8 row_mask:0xf bank_mask:0xc
	v_add_f32_dpp v105, v81, v81 row_ror:8 row_mask:0xf bank_mask:0x3
	v_add_f32_dpp v61, v61, v61 row_ror:8 row_mask:0xf bank_mask:0xc
	v_add_f32_dpp v61, v82, v82 row_ror:8 row_mask:0xf bank_mask:0x3
	v_add_f32_dpp v103, v103, v103 row_ror:4 row_mask:0xf bank_mask:0xa
	v_add_f32_dpp v103, v83, v83 row_ror:12 row_mask:0xf bank_mask:0x5
	v_add_f32_dpp v104, v104, v104 row_ror:4 row_mask:0xf bank_mask:0xa
	v_add_f32_dpp v104, v100, v100 row_ror:12 row_mask:0xf bank_mask:0x5
	v_add_f32_dpp v105, v105, v105 row_ror:4 row_mask:0xf bank_mask:0xa
	v_add_f32_dpp v105, v101, v101 row_ror:12 row_mask:0xf bank_mask:0x5
	v_add_f32_dpp v61, v61, v61 row_ror:4 row_mask:0xf bank_mask:0xa
	v_add_f32_dpp v61, v102, v102 row_ror:12 row_mask:0xf bank_mask:0x5
	v_cndmask_b32_e64 v62, v105, v103, s[38:39]
	v_cndmask_b32_e64 v63, v103, v105, s[38:39]
	v_cndmask_b32_e64 v64, v61, v104, s[38:39]
	v_cndmask_b32_e64 v65, v104, v61, s[38:39]
	v_add_f32_dpp v62, v63, v62 quad_perm:[2,3,0,1] row_mask:0xf bank_mask:0xf bound_ctrl:1
	s_nop 0
	v_add_f32_dpp v63, v65, v64 quad_perm:[2,3,0,1] row_mask:0xf bank_mask:0xf bound_ctrl:1
	v_cndmask_b32_e64 v65, v63, v62, s[40:41]
	v_cndmask_b32_e64 v62, v62, v63, s[40:41]
	s_nop 1
	v_add_f32_dpp v62, v62, v65 quad_perm:[1,0,3,2] row_mask:0xf bank_mask:0xf bound_ctrl:1
	v_cvt_pk_bf16_f32 v62, v62, v62
	global_store_short v[2:3], v62, off
	v_lshl_add_u64 v[2:3], v[2:3], 0, s[84:85]
	v_fma_mix_f32 v12, v6, v36, v180 op_sel_hi:[0,1,0]
	v_fma_mix_f32 v12, v7, v36, v12 op_sel:[0,1,0] op_sel_hi:[0,1,0]
	v_fma_mix_f32 v12, v8, v37, v12 op_sel_hi:[0,1,0]
	v_fma_mix_f32 v12, v9, v37, v12 op_sel:[0,1,0] op_sel_hi:[0,1,0]
	v_pk_mul_f32 v[48:49], v[6:7], v[32:33]
	v_pk_mul_f32 v[50:51], v[8:9], v[34:35]
	v_add_f32_dpp v12, v12, v12 row_ror:1 row_mask:0xf bank_mask:0xf bound_ctrl:1
	v_fma_mix_f32 v52, v6, v22, v180 op_sel_hi:[0,1,0]
	v_fma_mix_f32 v52, v7, v22, v52 op_sel:[0,1,0] op_sel_hi:[0,1,0]
	v_add_f32_dpp v12, v12, v12 row_ror:2 row_mask:0xf bank_mask:0xf bound_ctrl:1
	v_pk_fma_f32 v[48:49], v[44:45], v[66:67], v[48:49] op_sel:[0,1,0]
	v_pk_fma_f32 v[50:51], v[46:47], v[66:67], v[50:51] op_sel:[0,1,0]
	v_add_f32_dpp v12, v12, v12 row_ror:4 row_mask:0xf bank_mask:0xf bound_ctrl:1
	v_fma_mix_f32 v52, v8, v23, v52 op_sel_hi:[0,1,0]
	v_fma_mix_f32 v52, v9, v23, v52 op_sel:[0,1,0] op_sel_hi:[0,1,0]
	v_add_f32_dpp v12, v12, v12 row_ror:8 row_mask:0xf bank_mask:0xf bound_ctrl:1
	v_pk_fma_f32 v[6:7], v[40:41], v[12:13], v[48:49] op_sel_hi:[1,0,1] neg_lo:[1,0,0] neg_hi:[1,0,0]
	v_pk_fma_f32 v[8:9], v[42:43], v[12:13], v[50:51] op_sel_hi:[1,0,1] neg_lo:[1,0,0] neg_hi:[1,0,0]
	s_waitcnt lgkmcnt(1)
	v_fma_mix_f32 v12, v6, v88, v180 op_sel_hi:[0,1,0]
	v_fma_mix_f32 v12, v7, v88, v12 op_sel:[0,1,0] op_sel_hi:[0,1,0]
	v_fma_mix_f32 v12, v8, v89, v12 op_sel_hi:[0,1,0]
	v_fma_mix_f32 v12, v9, v89, v12 op_sel:[0,1,0] op_sel_hi:[0,1,0]
	v_pk_mul_f32 v[48:49], v[6:7], v[84:85]
	v_pk_mul_f32 v[50:51], v[8:9], v[86:87]
	v_add_f32_dpp v12, v12, v12 row_ror:1 row_mask:0xf bank_mask:0xf bound_ctrl:1
	v_fma_mix_f32 v53, v6, v38, v180 op_sel_hi:[0,1,0]
	v_fma_mix_f32 v53, v7, v38, v53 op_sel:[0,1,0] op_sel_hi:[0,1,0]
	v_add_f32_dpp v12, v12, v12 row_ror:2 row_mask:0xf bank_mask:0xf bound_ctrl:1
	v_pk_fma_f32 v[48:49], v[96:97], v[68:69], v[48:49] op_sel_hi:[1,0,1]
	v_pk_fma_f32 v[50:51], v[98:99], v[68:69], v[50:51] op_sel_hi:[1,0,1]
	v_add_f32_dpp v12, v12, v12 row_ror:4 row_mask:0xf bank_mask:0xf bound_ctrl:1
	v_fma_mix_f32 v53, v8, v39, v53 op_sel_hi:[0,1,0]
	v_fma_mix_f32 v53, v9, v39, v53 op_sel:[0,1,0] op_sel_hi:[0,1,0]
	v_add_f32_dpp v12, v12, v12 row_ror:8 row_mask:0xf bank_mask:0xf bound_ctrl:1
	v_pk_fma_f32 v[6:7], v[92:93], v[12:13], v[48:49] op_sel_hi:[1,0,1] neg_lo:[1,0,0] neg_hi:[1,0,0]
	v_pk_fma_f32 v[8:9], v[94:95], v[12:13], v[50:51] op_sel_hi:[1,0,1] neg_lo:[1,0,0] neg_hi:[1,0,0]
	ds_read_b128 v[20:23], v10 offset:53504
	ds_read_b128 v[16:19], v10 offset:53248
	ds_read_b128 v[28:31], v10 offset:54016
	ds_read_b128 v[24:27], v10 offset:53760
	ds_read_b128 v[36:39], v10 offset:54528
	ds_read_b128 v[32:35], v10 offset:54272
	ds_read_b128 v[44:47], v10 offset:55040
	ds_read_b128 v[40:43], v10 offset:54784
	v_fma_mix_f32 v12, v6, v110, v180 op_sel_hi:[0,1,0]
	v_fma_mix_f32 v12, v7, v110, v12 op_sel:[0,1,0] op_sel_hi:[0,1,0]
	v_fma_mix_f32 v12, v8, v111, v12 op_sel_hi:[0,1,0]
	v_fma_mix_f32 v12, v9, v111, v12 op_sel:[0,1,0] op_sel_hi:[0,1,0]
	v_pk_mul_f32 v[48:49], v[6:7], v[106:107]
	v_pk_mul_f32 v[50:51], v[8:9], v[108:109]
	v_add_f32_dpp v12, v12, v12 row_ror:1 row_mask:0xf bank_mask:0xf bound_ctrl:1
	v_fma_mix_f32 v54, v6, v90, v180 op_sel_hi:[0,1,0]
	v_fma_mix_f32 v54, v7, v90, v54 op_sel:[0,1,0] op_sel_hi:[0,1,0]
	v_add_f32_dpp v12, v12, v12 row_ror:2 row_mask:0xf bank_mask:0xf bound_ctrl:1
	v_pk_fma_f32 v[48:49], v[118:119], v[68:69], v[48:49] op_sel:[0,1,0]
	v_pk_fma_f32 v[50:51], v[120:121], v[68:69], v[50:51] op_sel:[0,1,0]
	v_add_f32_dpp v12, v12, v12 row_ror:4 row_mask:0xf bank_mask:0xf bound_ctrl:1
	v_fma_mix_f32 v54, v8, v91, v54 op_sel_hi:[0,1,0]
	v_fma_mix_f32 v54, v9, v91, v54 op_sel:[0,1,0] op_sel_hi:[0,1,0]
	v_add_f32_dpp v12, v12, v12 row_ror:8 row_mask:0xf bank_mask:0xf bound_ctrl:1
	v_pk_fma_f32 v[6:7], v[114:115], v[12:13], v[48:49] op_sel_hi:[1,0,1] neg_lo:[1,0,0] neg_hi:[1,0,0]
	v_pk_fma_f32 v[8:9], v[116:117], v[12:13], v[50:51] op_sel_hi:[1,0,1] neg_lo:[1,0,0] neg_hi:[1,0,0]
	s_waitcnt lgkmcnt(0)
	v_fma_mix_f32 v12, v6, v20, v180 op_sel_hi:[0,1,0]
	v_fma_mix_f32 v12, v7, v20, v12 op_sel:[0,1,0] op_sel_hi:[0,1,0]
	v_fma_mix_f32 v12, v8, v21, v12 op_sel_hi:[0,1,0]
	v_fma_mix_f32 v12, v9, v21, v12 op_sel:[0,1,0] op_sel_hi:[0,1,0]
	v_pk_mul_f32 v[48:49], v[6:7], v[16:17]
	v_pk_mul_f32 v[50:51], v[8:9], v[18:19]
	v_add_f32_dpp v12, v12, v12 row_ror:1 row_mask:0xf bank_mask:0xf bound_ctrl:1
	v_fma_mix_f32 v55, v6, v112, v180 op_sel_hi:[0,1,0]
	v_fma_mix_f32 v55, v7, v112, v55 op_sel:[0,1,0] op_sel_hi:[0,1,0]
	v_add_f32_dpp v12, v12, v12 row_ror:2 row_mask:0xf bank_mask:0xf bound_ctrl:1
	v_pk_fma_f32 v[48:49], v[28:29], v[70:71], v[48:49] op_sel_hi:[1,0,1]
	v_pk_fma_f32 v[50:51], v[30:31], v[70:71], v[50:51] op_sel_hi:[1,0,1]
	v_add_f32_dpp v12, v12, v12 row_ror:4 row_mask:0xf bank_mask:0xf bound_ctrl:1
	v_fma_mix_f32 v55, v8, v113, v55 op_sel_hi:[0,1,0]
	v_fma_mix_f32 v55, v9, v113, v55 op_sel:[0,1,0] op_sel_hi:[0,1,0]
	v_add_f32_dpp v12, v12, v12 row_ror:8 row_mask:0xf bank_mask:0xf bound_ctrl:1
	v_pk_fma_f32 v[6:7], v[24:25], v[12:13], v[48:49] op_sel_hi:[1,0,1] neg_lo:[1,0,0] neg_hi:[1,0,0]
	v_pk_fma_f32 v[8:9], v[26:27], v[12:13], v[50:51] op_sel_hi:[1,0,1] neg_lo:[1,0,0] neg_hi:[1,0,0]
	ds_read_b128 v[88:91], v10 offset:55552
	ds_read_b128 v[84:87], v10 offset:55296
	ds_read_b128 v[96:99], v10 offset:56064
	ds_read_b128 v[92:95], v10 offset:55808
	ds_read_b128 v[110:113], v10 offset:56576
	ds_read_b128 v[106:109], v10 offset:56320
	ds_read_b128 v[118:121], v10 offset:57088
	ds_read_b128 v[114:117], v10 offset:56832
	ds_read_b128 v[66:69], v11 offset:3584
	v_fma_mix_f32 v12, v6, v36, v180 op_sel_hi:[0,1,0]
	v_fma_mix_f32 v12, v7, v36, v12 op_sel:[0,1,0] op_sel_hi:[0,1,0]
	v_fma_mix_f32 v12, v8, v37, v12 op_sel_hi:[0,1,0]
	v_fma_mix_f32 v12, v9, v37, v12 op_sel:[0,1,0] op_sel_hi:[0,1,0]
	v_pk_mul_f32 v[48:49], v[6:7], v[32:33]
	v_pk_mul_f32 v[50:51], v[8:9], v[34:35]
	v_add_f32_dpp v12, v12, v12 row_ror:1 row_mask:0xf bank_mask:0xf bound_ctrl:1
	v_fma_mix_f32 v56, v6, v22, v180 op_sel_hi:[0,1,0]
	v_fma_mix_f32 v56, v7, v22, v56 op_sel:[0,1,0] op_sel_hi:[0,1,0]
	v_add_f32_dpp v12, v12, v12 row_ror:2 row_mask:0xf bank_mask:0xf bound_ctrl:1
	v_pk_fma_f32 v[48:49], v[44:45], v[70:71], v[48:49] op_sel:[0,1,0]
	v_pk_fma_f32 v[50:51], v[46:47], v[70:71], v[50:51] op_sel:[0,1,0]
	v_add_f32_dpp v12, v12, v12 row_ror:4 row_mask:0xf bank_mask:0xf bound_ctrl:1
	v_fma_mix_f32 v56, v8, v23, v56 op_sel_hi:[0,1,0]
	v_fma_mix_f32 v56, v9, v23, v56 op_sel:[0,1,0] op_sel_hi:[0,1,0]
	v_add_f32_dpp v12, v12, v12 row_ror:8 row_mask:0xf bank_mask:0xf bound_ctrl:1
	v_pk_fma_f32 v[6:7], v[40:41], v[12:13], v[48:49] op_sel_hi:[1,0,1] neg_lo:[1,0,0] neg_hi:[1,0,0]
	v_pk_fma_f32 v[8:9], v[42:43], v[12:13], v[50:51] op_sel_hi:[1,0,1] neg_lo:[1,0,0] neg_hi:[1,0,0]
	s_waitcnt lgkmcnt(1)
	v_fma_mix_f32 v12, v6, v88, v180 op_sel_hi:[0,1,0]
	v_fma_mix_f32 v12, v7, v88, v12 op_sel:[0,1,0] op_sel_hi:[0,1,0]
	v_fma_mix_f32 v12, v8, v89, v12 op_sel_hi:[0,1,0]
	v_fma_mix_f32 v12, v9, v89, v12 op_sel:[0,1,0] op_sel_hi:[0,1,0]
	v_pk_mul_f32 v[48:49], v[6:7], v[84:85]
	v_pk_mul_f32 v[50:51], v[8:9], v[86:87]
	v_add_f32_dpp v12, v12, v12 row_ror:1 row_mask:0xf bank_mask:0xf bound_ctrl:1
	v_fma_mix_f32 v57, v6, v38, v180 op_sel_hi:[0,1,0]
	v_fma_mix_f32 v57, v7, v38, v57 op_sel:[0,1,0] op_sel_hi:[0,1,0]
	v_add_f32_dpp v12, v12, v12 row_ror:2 row_mask:0xf bank_mask:0xf bound_ctrl:1
	v_pk_fma_f32 v[48:49], v[96:97], v[72:73], v[48:49] op_sel_hi:[1,0,1]
	v_pk_fma_f32 v[50:51], v[98:99], v[72:73], v[50:51] op_sel_hi:[1,0,1]
	v_add_f32_dpp v12, v12, v12 row_ror:4 row_mask:0xf bank_mask:0xf bound_ctrl:1
	v_fma_mix_f32 v57, v8, v39, v57 op_sel_hi:[0,1,0]
	v_fma_mix_f32 v57, v9, v39, v57 op_sel:[0,1,0] op_sel_hi:[0,1,0]
	v_add_f32_dpp v12, v12, v12 row_ror:8 row_mask:0xf bank_mask:0xf bound_ctrl:1
	v_pk_fma_f32 v[6:7], v[92:93], v[12:13], v[48:49] op_sel_hi:[1,0,1] neg_lo:[1,0,0] neg_hi:[1,0,0]
	v_pk_fma_f32 v[8:9], v[94:95], v[12:13], v[50:51] op_sel_hi:[1,0,1] neg_lo:[1,0,0] neg_hi:[1,0,0]
	ds_read_b128 v[20:23], v10 offset:57600
	ds_read_b128 v[16:19], v10 offset:57344
	ds_read_b128 v[28:31], v10 offset:58112
	ds_read_b128 v[24:27], v10 offset:57856
	ds_read_b128 v[36:39], v10 offset:58624
	ds_read_b128 v[32:35], v10 offset:58368
	ds_read_b128 v[44:47], v10 offset:59136
	ds_read_b128 v[40:43], v10 offset:58880
	v_fma_mix_f32 v12, v6, v110, v180 op_sel_hi:[0,1,0]
	v_fma_mix_f32 v12, v7, v110, v12 op_sel:[0,1,0] op_sel_hi:[0,1,0]
	v_fma_mix_f32 v12, v8, v111, v12 op_sel_hi:[0,1,0]
	v_fma_mix_f32 v12, v9, v111, v12 op_sel:[0,1,0] op_sel_hi:[0,1,0]
	v_pk_mul_f32 v[48:49], v[6:7], v[106:107]
	v_pk_mul_f32 v[50:51], v[8:9], v[108:109]
	v_add_f32_dpp v12, v12, v12 row_ror:1 row_mask:0xf bank_mask:0xf bound_ctrl:1
	v_fma_mix_f32 v81, v6, v90, v180 op_sel_hi:[0,1,0]
	v_fma_mix_f32 v81, v7, v90, v81 op_sel:[0,1,0] op_sel_hi:[0,1,0]
	v_add_f32_dpp v12, v12, v12 row_ror:2 row_mask:0xf bank_mask:0xf bound_ctrl:1
	v_pk_fma_f32 v[48:49], v[118:119], v[72:73], v[48:49] op_sel:[0,1,0]
	v_pk_fma_f32 v[50:51], v[120:121], v[72:73], v[50:51] op_sel:[0,1,0]
	v_add_f32_dpp v12, v12, v12 row_ror:4 row_mask:0xf bank_mask:0xf bound_ctrl:1
	v_fma_mix_f32 v81, v8, v91, v81 op_sel_hi:[0,1,0]
	v_fma_mix_f32 v81, v9, v91, v81 op_sel:[0,1,0] op_sel_hi:[0,1,0]
	v_add_f32_dpp v12, v12, v12 row_ror:8 row_mask:0xf bank_mask:0xf bound_ctrl:1
	v_pk_fma_f32 v[6:7], v[114:115], v[12:13], v[48:49] op_sel_hi:[1,0,1] neg_lo:[1,0,0] neg_hi:[1,0,0]
	v_pk_fma_f32 v[8:9], v[116:117], v[12:13], v[50:51] op_sel_hi:[1,0,1] neg_lo:[1,0,0] neg_hi:[1,0,0]
	s_waitcnt lgkmcnt(0)
	v_fma_mix_f32 v12, v6, v20, v180 op_sel_hi:[0,1,0]
	v_fma_mix_f32 v12, v7, v20, v12 op_sel:[0,1,0] op_sel_hi:[0,1,0]
	v_fma_mix_f32 v12, v8, v21, v12 op_sel_hi:[0,1,0]
	v_fma_mix_f32 v12, v9, v21, v12 op_sel:[0,1,0] op_sel_hi:[0,1,0]
	v_pk_mul_f32 v[48:49], v[6:7], v[16:17]
	v_pk_mul_f32 v[50:51], v[8:9], v[18:19]
	v_add_f32_dpp v12, v12, v12 row_ror:1 row_mask:0xf bank_mask:0xf bound_ctrl:1
	v_fma_mix_f32 v82, v6, v112, v180 op_sel_hi:[0,1,0]
	v_fma_mix_f32 v82, v7, v112, v82 op_sel:[0,1,0] op_sel_hi:[0,1,0]
	v_add_f32_dpp v12, v12, v12 row_ror:2 row_mask:0xf bank_mask:0xf bound_ctrl:1
	v_pk_fma_f32 v[48:49], v[28:29], v[66:67], v[48:49] op_sel_hi:[1,0,1]
	v_pk_fma_f32 v[50:51], v[30:31], v[66:67], v[50:51] op_sel_hi:[1,0,1]
	v_add_f32_dpp v12, v12, v12 row_ror:4 row_mask:0xf bank_mask:0xf bound_ctrl:1
	v_fma_mix_f32 v82, v8, v113, v82 op_sel_hi:[0,1,0]
	v_fma_mix_f32 v82, v9, v113, v82 op_sel:[0,1,0] op_sel_hi:[0,1,0]
	v_add_f32_dpp v12, v12, v12 row_ror:8 row_mask:0xf bank_mask:0xf bound_ctrl:1
	v_pk_fma_f32 v[6:7], v[24:25], v[12:13], v[48:49] op_sel_hi:[1,0,1] neg_lo:[1,0,0] neg_hi:[1,0,0]
	v_pk_fma_f32 v[8:9], v[26:27], v[12:13], v[50:51] op_sel_hi:[1,0,1] neg_lo:[1,0,0] neg_hi:[1,0,0]
	ds_read_b128 v[88:91], v10 offset:59648
	ds_read_b128 v[84:87], v10 offset:59392
	ds_read_b128 v[96:99], v10 offset:60160
	ds_read_b128 v[92:95], v10 offset:59904
	ds_read_b128 v[110:113], v10 offset:60672
	ds_read_b128 v[106:109], v10 offset:60416
	ds_read_b128 v[118:121], v10 offset:61184
	ds_read_b128 v[114:117], v10 offset:60928
	ds_read_b128 v[70:73], v11 offset:3840
	v_fma_mix_f32 v12, v6, v36, v180 op_sel_hi:[0,1,0]
	v_fma_mix_f32 v12, v7, v36, v12 op_sel:[0,1,0] op_sel_hi:[0,1,0]
	v_fma_mix_f32 v12, v8, v37, v12 op_sel_hi:[0,1,0]
	v_fma_mix_f32 v12, v9, v37, v12 op_sel:[0,1,0] op_sel_hi:[0,1,0]
	v_pk_mul_f32 v[48:49], v[6:7], v[32:33]
	v_pk_mul_f32 v[50:51], v[8:9], v[34:35]
	v_add_f32_dpp v12, v12, v12 row_ror:1 row_mask:0xf bank_mask:0xf bound_ctrl:1
	v_fma_mix_f32 v83, v6, v22, v180 op_sel_hi:[0,1,0]
	v_fma_mix_f32 v83, v7, v22, v83 op_sel:[0,1,0] op_sel_hi:[0,1,0]
	v_add_f32_dpp v12, v12, v12 row_ror:2 row_mask:0xf bank_mask:0xf bound_ctrl:1
	v_pk_fma_f32 v[48:49], v[44:45], v[66:67], v[48:49] op_sel:[0,1,0]
	v_pk_fma_f32 v[50:51], v[46:47], v[66:67], v[50:51] op_sel:[0,1,0]
	v_add_f32_dpp v12, v12, v12 row_ror:4 row_mask:0xf bank_mask:0xf bound_ctrl:1
	v_fma_mix_f32 v83, v8, v23, v83 op_sel_hi:[0,1,0]
	v_fma_mix_f32 v83, v9, v23, v83 op_sel:[0,1,0] op_sel_hi:[0,1,0]
	v_add_f32_dpp v12, v12, v12 row_ror:8 row_mask:0xf bank_mask:0xf bound_ctrl:1
	v_pk_fma_f32 v[6:7], v[40:41], v[12:13], v[48:49] op_sel_hi:[1,0,1] neg_lo:[1,0,0] neg_hi:[1,0,0]
	v_pk_fma_f32 v[8:9], v[42:43], v[12:13], v[50:51] op_sel_hi:[1,0,1] neg_lo:[1,0,0] neg_hi:[1,0,0]
	s_waitcnt lgkmcnt(1)
	v_fma_mix_f32 v12, v6, v88, v180 op_sel_hi:[0,1,0]
	v_fma_mix_f32 v12, v7, v88, v12 op_sel:[0,1,0] op_sel_hi:[0,1,0]
	v_fma_mix_f32 v12, v8, v89, v12 op_sel_hi:[0,1,0]
	v_fma_mix_f32 v12, v9, v89, v12 op_sel:[0,1,0] op_sel_hi:[0,1,0]
	v_pk_mul_f32 v[48:49], v[6:7], v[84:85]
	v_pk_mul_f32 v[50:51], v[8:9], v[86:87]
	v_add_f32_dpp v12, v12, v12 row_ror:1 row_mask:0xf bank_mask:0xf bound_ctrl:1
	v_fma_mix_f32 v100, v6, v38, v180 op_sel_hi:[0,1,0]
	v_fma_mix_f32 v100, v7, v38, v100 op_sel:[0,1,0] op_sel_hi:[0,1,0]
	v_add_f32_dpp v12, v12, v12 row_ror:2 row_mask:0xf bank_mask:0xf bound_ctrl:1
	v_pk_fma_f32 v[48:49], v[96:97], v[68:69], v[48:49] op_sel_hi:[1,0,1]
	v_pk_fma_f32 v[50:51], v[98:99], v[68:69], v[50:51] op_sel_hi:[1,0,1]
	v_add_f32_dpp v12, v12, v12 row_ror:4 row_mask:0xf bank_mask:0xf bound_ctrl:1
	v_fma_mix_f32 v100, v8, v39, v100 op_sel_hi:[0,1,0]
	v_fma_mix_f32 v100, v9, v39, v100 op_sel:[0,1,0] op_sel_hi:[0,1,0]
	v_add_f32_dpp v12, v12, v12 row_ror:8 row_mask:0xf bank_mask:0xf bound_ctrl:1
	v_pk_fma_f32 v[6:7], v[92:93], v[12:13], v[48:49] op_sel_hi:[1,0,1] neg_lo:[1,0,0] neg_hi:[1,0,0]
	v_pk_fma_f32 v[8:9], v[94:95], v[12:13], v[50:51] op_sel_hi:[1,0,1] neg_lo:[1,0,0] neg_hi:[1,0,0]
	ds_read_b128 v[20:23], v10 offset:61696
	ds_read_b128 v[16:19], v10 offset:61440
	ds_read_b128 v[28:31], v10 offset:62208
	ds_read_b128 v[24:27], v10 offset:61952
	ds_read_b128 v[36:39], v10 offset:62720
	ds_read_b128 v[32:35], v10 offset:62464
	ds_read_b128 v[44:47], v10 offset:63232
	ds_read_b128 v[40:43], v10 offset:62976
	v_fma_mix_f32 v12, v6, v110, v180 op_sel_hi:[0,1,0]
	v_fma_mix_f32 v12, v7, v110, v12 op_sel:[0,1,0] op_sel_hi:[0,1,0]
	v_fma_mix_f32 v12, v8, v111, v12 op_sel_hi:[0,1,0]
	v_fma_mix_f32 v12, v9, v111, v12 op_sel:[0,1,0] op_sel_hi:[0,1,0]
	v_pk_mul_f32 v[48:49], v[6:7], v[106:107]
	v_pk_mul_f32 v[50:51], v[8:9], v[108:109]
	v_add_f32_dpp v12, v12, v12 row_ror:1 row_mask:0xf bank_mask:0xf bound_ctrl:1
	v_fma_mix_f32 v101, v6, v90, v180 op_sel_hi:[0,1,0]
	v_fma_mix_f32 v101, v7, v90, v101 op_sel:[0,1,0] op_sel_hi:[0,1,0]
	v_add_f32_dpp v12, v12, v12 row_ror:2 row_mask:0xf bank_mask:0xf bound_ctrl:1
	v_pk_fma_f32 v[48:49], v[118:119], v[68:69], v[48:49] op_sel:[0,1,0]
	v_pk_fma_f32 v[50:51], v[120:121], v[68:69], v[50:51] op_sel:[0,1,0]
	v_add_f32_dpp v12, v12, v12 row_ror:4 row_mask:0xf bank_mask:0xf bound_ctrl:1
	v_fma_mix_f32 v101, v8, v91, v101 op_sel_hi:[0,1,0]
	v_fma_mix_f32 v101, v9, v91, v101 op_sel:[0,1,0] op_sel_hi:[0,1,0]
	v_add_f32_dpp v12, v12, v12 row_ror:8 row_mask:0xf bank_mask:0xf bound_ctrl:1
	v_pk_fma_f32 v[6:7], v[114:115], v[12:13], v[48:49] op_sel_hi:[1,0,1] neg_lo:[1,0,0] neg_hi:[1,0,0]
	v_pk_fma_f32 v[8:9], v[116:117], v[12:13], v[50:51] op_sel_hi:[1,0,1] neg_lo:[1,0,0] neg_hi:[1,0,0]
	s_waitcnt lgkmcnt(0)
	v_fma_mix_f32 v12, v6, v20, v180 op_sel_hi:[0,1,0]
	v_fma_mix_f32 v12, v7, v20, v12 op_sel:[0,1,0] op_sel_hi:[0,1,0]
	v_fma_mix_f32 v12, v8, v21, v12 op_sel_hi:[0,1,0]
	v_fma_mix_f32 v12, v9, v21, v12 op_sel:[0,1,0] op_sel_hi:[0,1,0]
	v_pk_mul_f32 v[48:49], v[6:7], v[16:17]
	v_pk_mul_f32 v[50:51], v[8:9], v[18:19]
	v_add_f32_dpp v12, v12, v12 row_ror:1 row_mask:0xf bank_mask:0xf bound_ctrl:1
	v_fma_mix_f32 v102, v6, v112, v180 op_sel_hi:[0,1,0]
	v_fma_mix_f32 v102, v7, v112, v102 op_sel:[0,1,0] op_sel_hi:[0,1,0]
	v_add_f32_dpp v12, v12, v12 row_ror:2 row_mask:0xf bank_mask:0xf bound_ctrl:1
	v_pk_fma_f32 v[48:49], v[28:29], v[70:71], v[48:49] op_sel_hi:[1,0,1]
	v_pk_fma_f32 v[50:51], v[30:31], v[70:71], v[50:51] op_sel_hi:[1,0,1]
	v_add_f32_dpp v12, v12, v12 row_ror:4 row_mask:0xf bank_mask:0xf bound_ctrl:1
	v_fma_mix_f32 v102, v8, v113, v102 op_sel_hi:[0,1,0]
	v_fma_mix_f32 v102, v9, v113, v102 op_sel:[0,1,0] op_sel_hi:[0,1,0]
	v_add_f32_dpp v12, v12, v12 row_ror:8 row_mask:0xf bank_mask:0xf bound_ctrl:1
	v_pk_fma_f32 v[6:7], v[24:25], v[12:13], v[48:49] op_sel_hi:[1,0,1] neg_lo:[1,0,0] neg_hi:[1,0,0]
	v_pk_fma_f32 v[8:9], v[26:27], v[12:13], v[50:51] op_sel_hi:[1,0,1] neg_lo:[1,0,0] neg_hi:[1,0,0]
	ds_read_b128 v[88:91], v10 offset:63744
	ds_read_b128 v[84:87], v10 offset:63488
	ds_read_b128 v[96:99], v10 offset:64256
	ds_read_b128 v[92:95], v10 offset:64000
	ds_read_b128 v[110:113], v10 offset:64768
	ds_read_b128 v[106:109], v10 offset:64512
	ds_read_b128 v[118:121], v10 offset:65280
	ds_read_b128 v[114:117], v10 offset:65024
	v_fma_mix_f32 v12, v6, v36, v180 op_sel_hi:[0,1,0]
	v_fma_mix_f32 v12, v7, v36, v12 op_sel:[0,1,0] op_sel_hi:[0,1,0]
	v_fma_mix_f32 v12, v8, v37, v12 op_sel_hi:[0,1,0]
	v_fma_mix_f32 v12, v9, v37, v12 op_sel:[0,1,0] op_sel_hi:[0,1,0]
	v_pk_mul_f32 v[48:49], v[6:7], v[32:33]
	v_pk_mul_f32 v[50:51], v[8:9], v[34:35]
	v_add_f32_dpp v12, v12, v12 row_ror:1 row_mask:0xf bank_mask:0xf bound_ctrl:1
	v_fma_mix_f32 v103, v6, v22, v180 op_sel_hi:[0,1,0]
	v_fma_mix_f32 v103, v7, v22, v103 op_sel:[0,1,0] op_sel_hi:[0,1,0]
	v_add_f32_dpp v12, v12, v12 row_ror:2 row_mask:0xf bank_mask:0xf bound_ctrl:1
	v_pk_fma_f32 v[48:49], v[44:45], v[70:71], v[48:49] op_sel:[0,1,0]
	v_pk_fma_f32 v[50:51], v[46:47], v[70:71], v[50:51] op_sel:[0,1,0]
	v_add_f32_dpp v12, v12, v12 row_ror:4 row_mask:0xf bank_mask:0xf bound_ctrl:1
	v_fma_mix_f32 v103, v8, v23, v103 op_sel_hi:[0,1,0]
	v_fma_mix_f32 v103, v9, v23, v103 op_sel:[0,1,0] op_sel_hi:[0,1,0]
	v_add_f32_dpp v12, v12, v12 row_ror:8 row_mask:0xf bank_mask:0xf bound_ctrl:1
	v_pk_fma_f32 v[6:7], v[40:41], v[12:13], v[48:49] op_sel_hi:[1,0,1] neg_lo:[1,0,0] neg_hi:[1,0,0]
	v_pk_fma_f32 v[8:9], v[42:43], v[12:13], v[50:51] op_sel_hi:[1,0,1] neg_lo:[1,0,0] neg_hi:[1,0,0]
	s_waitcnt lgkmcnt(0)
	v_fma_mix_f32 v12, v6, v88, v180 op_sel_hi:[0,1,0]
	v_fma_mix_f32 v12, v7, v88, v12 op_sel:[0,1,0] op_sel_hi:[0,1,0]
	v_fma_mix_f32 v12, v8, v89, v12 op_sel_hi:[0,1,0]
	v_fma_mix_f32 v12, v9, v89, v12 op_sel:[0,1,0] op_sel_hi:[0,1,0]
	v_pk_mul_f32 v[48:49], v[6:7], v[84:85]
	v_pk_mul_f32 v[50:51], v[8:9], v[86:87]
	v_add_f32_dpp v12, v12, v12 row_ror:1 row_mask:0xf bank_mask:0xf bound_ctrl:1
	v_fma_mix_f32 v104, v6, v38, v180 op_sel_hi:[0,1,0]
	v_fma_mix_f32 v104, v7, v38, v104 op_sel:[0,1,0] op_sel_hi:[0,1,0]
	v_add_f32_dpp v12, v12, v12 row_ror:2 row_mask:0xf bank_mask:0xf bound_ctrl:1
	v_pk_fma_f32 v[48:49], v[96:97], v[72:73], v[48:49] op_sel_hi:[1,0,1]
	v_pk_fma_f32 v[50:51], v[98:99], v[72:73], v[50:51] op_sel_hi:[1,0,1]
	v_add_f32_dpp v12, v12, v12 row_ror:4 row_mask:0xf bank_mask:0xf bound_ctrl:1
	v_fma_mix_f32 v104, v8, v39, v104 op_sel_hi:[0,1,0]
	v_fma_mix_f32 v104, v9, v39, v104 op_sel:[0,1,0] op_sel_hi:[0,1,0]
	v_add_f32_dpp v12, v12, v12 row_ror:8 row_mask:0xf bank_mask:0xf bound_ctrl:1
	v_pk_fma_f32 v[6:7], v[92:93], v[12:13], v[48:49] op_sel_hi:[1,0,1] neg_lo:[1,0,0] neg_hi:[1,0,0]
	v_pk_fma_f32 v[8:9], v[94:95], v[12:13], v[50:51] op_sel_hi:[1,0,1] neg_lo:[1,0,0] neg_hi:[1,0,0]
	s_waitcnt lgkmcnt(0)
	s_barrier
	v_xor_b32_e32 v10, 0x10000, v10
	v_xor_b32_e32 v11, 0x1000, v11
	ds_read_b128 v[66:69], v11 offset:0
	ds_read_b128 v[20:23], v10 offset:256
	ds_read_b128 v[16:19], v10 offset:0
	ds_read_b128 v[28:31], v10 offset:768
	ds_read_b128 v[24:27], v10 offset:512
	ds_read_b128 v[36:39], v10 offset:1280
	ds_read_b128 v[32:35], v10 offset:1024
	ds_read_b128 v[44:47], v10 offset:1792
	ds_read_b128 v[40:43], v10 offset:1536
	v_fma_mix_f32 v12, v6, v110, v180 op_sel_hi:[0,1,0]
	v_fma_mix_f32 v12, v7, v110, v12 op_sel:[0,1,0] op_sel_hi:[0,1,0]
	v_fma_mix_f32 v12, v8, v111, v12 op_sel_hi:[0,1,0]
	v_fma_mix_f32 v12, v9, v111, v12 op_sel:[0,1,0] op_sel_hi:[0,1,0]
	v_pk_mul_f32 v[48:49], v[6:7], v[106:107]
	v_pk_mul_f32 v[50:51], v[8:9], v[108:109]
	v_add_f32_dpp v12, v12, v12 row_ror:1 row_mask:0xf bank_mask:0xf bound_ctrl:1
	v_fma_mix_f32 v105, v6, v90, v180 op_sel_hi:[0,1,0]
	v_fma_mix_f32 v105, v7, v90, v105 op_sel:[0,1,0] op_sel_hi:[0,1,0]
	v_add_f32_dpp v12, v12, v12 row_ror:2 row_mask:0xf bank_mask:0xf bound_ctrl:1
	v_pk_fma_f32 v[48:49], v[118:119], v[72:73], v[48:49] op_sel:[0,1,0]
	v_pk_fma_f32 v[50:51], v[120:121], v[72:73], v[50:51] op_sel:[0,1,0]
	v_add_f32_dpp v12, v12, v12 row_ror:4 row_mask:0xf bank_mask:0xf bound_ctrl:1
	v_fma_mix_f32 v105, v8, v91, v105 op_sel_hi:[0,1,0]
	v_fma_mix_f32 v105, v9, v91, v105 op_sel:[0,1,0] op_sel_hi:[0,1,0]
	v_add_f32_dpp v12, v12, v12 row_ror:8 row_mask:0xf bank_mask:0xf bound_ctrl:1
	v_pk_fma_f32 v[6:7], v[114:115], v[12:13], v[48:49] op_sel_hi:[1,0,1] neg_lo:[1,0,0] neg_hi:[1,0,0]
	v_pk_fma_f32 v[8:9], v[116:117], v[12:13], v[50:51] op_sel_hi:[1,0,1] neg_lo:[1,0,0] neg_hi:[1,0,0]
	v_fma_mix_f32 v61, v6, v112, v180 op_sel_hi:[0,1,0]
	v_fma_mix_f32 v61, v7, v112, v61 op_sel:[0,1,0] op_sel_hi:[0,1,0]
	v_fma_mix_f32 v61, v8, v113, v61 op_sel_hi:[0,1,0]
	v_fma_mix_f32 v61, v9, v113, v61 op_sel:[0,1,0] op_sel_hi:[0,1,0]
	v_add_f32_dpp v83, v83, v83 row_ror:8 row_mask:0xf bank_mask:0xc
	v_add_f32_dpp v83, v52, v52 row_ror:8 row_mask:0xf bank_mask:0x3
	v_add_f32_dpp v100, v100, v100 row_ror:8 row_mask:0xf bank_mask:0xc
	v_add_f32_dpp v100, v53, v53 row_ror:8 row_mask:0xf bank_mask:0x3
	v_add_f32_dpp v101, v101, v101 row_ror:8 row_mask:0xf bank_mask:0xc
	v_add_f32_dpp v101, v54, v54 row_ror:8 row_mask:0xf bank_mask:0x3
	v_add_f32_dpp v102, v102, v102 row_ror:8 row_mask:0xf bank_mask:0xc
	v_add_f32_dpp v102, v55, v55 row_ror:8 row_mask:0xf bank_mask:0x3
	v_add_f32_dpp v103, v103, v103 row_ror:8 row_mask:0xf bank_mask:0xc
	v_add_f32_dpp v103, v56, v56 row_ror:8 row_mask:0xf bank_mask:0x3
	v_add_f32_dpp v104, v104, v104 row_ror:8 row_mask:0xf bank_mask:0xc
	v_add_f32_dpp v104, v57, v57 row_ror:8 row_mask:0xf bank_mask:0x3
	v_add_f32_dpp v105, v105, v105 row_ror:8 row_mask:0xf bank_mask:0xc
	v_add_f32_dpp v105, v81, v81 row_ror:8 row_mask:0xf bank_mask:0x3
	v_add_f32_dpp v61, v61, v61 row_ror:8 row_mask:0xf bank_mask:0xc
	v_add_f32_dpp v61, v82, v82 row_ror:8 row_mask:0xf bank_mask:0x3
	v_add_f32_dpp v103, v103, v103 row_ror:4 row_mask:0xf bank_mask:0xa
	v_add_f32_dpp v103, v83, v83 row_ror:12 row_mask:0xf bank_mask:0x5
	v_add_f32_dpp v104, v104, v104 row_ror:4 row_mask:0xf bank_mask:0xa
	v_add_f32_dpp v104, v100, v100 row_ror:12 row_mask:0xf bank_mask:0x5
	v_add_f32_dpp v105, v105, v105 row_ror:4 row_mask:0xf bank_mask:0xa
	v_add_f32_dpp v105, v101, v101 row_ror:12 row_mask:0xf bank_mask:0x5
	v_add_f32_dpp v61, v61, v61 row_ror:4 row_mask:0xf bank_mask:0xa
	v_add_f32_dpp v61, v102, v102 row_ror:12 row_mask:0xf bank_mask:0x5
	v_cndmask_b32_e64 v62, v105, v103, s[38:39]
	v_cndmask_b32_e64 v63, v103, v105, s[38:39]
	v_cndmask_b32_e64 v64, v61, v104, s[38:39]
	v_cndmask_b32_e64 v65, v104, v61, s[38:39]
	v_add_f32_dpp v62, v63, v62 quad_perm:[2,3,0,1] row_mask:0xf bank_mask:0xf bound_ctrl:1
	s_nop 0
	v_add_f32_dpp v63, v65, v64 quad_perm:[2,3,0,1] row_mask:0xf bank_mask:0xf bound_ctrl:1
	v_cndmask_b32_e64 v65, v63, v62, s[40:41]
	v_cndmask_b32_e64 v62, v62, v63, s[40:41]
	s_nop 1
	v_add_f32_dpp v62, v62, v65 quad_perm:[1,0,3,2] row_mask:0xf bank_mask:0xf bound_ctrl:1
	v_cvt_pk_bf16_f32 v62, v62, v62
	global_store_short v[2:3], v62, off
	s_cmp_lg_u32 s28, 0x800000
	s_cbranch_scc1 .Lscan_cons_chunk
	s_branch .LBB0_53
